# second SwiGLU epilogue half moved into the next unit's first trip (second super-phase slot), stores overlap next K-loop
# speedup vs baseline: 1.0109x; 1.0109x over previous
.LBB0_74:
	s_ashr_i32 s27, s26, 31
	s_lshl_b64 s[28:29], s[26:27], 19
	s_add_u32 s28, s3, s28
	s_addc_u32 s29, s35, s29
	s_and_b64 s[30:31], s[4:5], exec
	s_cselect_b32 s27, s29, s49
	s_cselect_b32 s68, s28, s48
	s_ashr_i32 s23, s22, 31
	s_lshl_b64 s[30:31], s[22:23], 19
	s_add_u32 s30, s50, s30
	s_addc_u32 s31, s51, s31
	s_and_b64 s[70:71], s[4:5], exec
	s_cselect_b32 s69, s31, s47
	s_cselect_b32 s70, s30, s46
	s_lshl_b32 s23, s44, 8
	v_add_u32_e32 v250, s23, v148
	s_add_u32 s71, s46, 0x100
	v_ashrrev_i32_e32 v251, 31, v250
	s_addc_u32 s74, s47, 0
	v_lshl_add_u64 v[144:145], v[250:251], 4, s[12:13]
	s_add_u32 s44, s48, 0x40080
	s_addc_u32 s45, s49, 0
	s_mov_b32 s75, -2
	s_mov_b64 s[46:47], 0
	s_cmp_eq_u32 s59, 1
	s_cbranch_scc1 .Lfa_0
	v_add_u32_e32 v153, s64, v147
	ds_read_b128 v[160:163], v153
	v_xor_b32_e32 v253, 64, v153
	ds_read_b128 v[164:167], v253
	ds_read_b128 v[168:171], v153 offset:2048
	ds_read_b128 v[172:175], v253 offset:2048
	v_add_u32_e32 v153, s65, v147
	ds_read_b128 v[176:179], v153
	v_xor_b32_e32 v253, 64, v153
	ds_read_b128 v[180:183], v253
	ds_read_b128 v[186:189], v153 offset:2048
	ds_read_b128 v[190:193], v253 offset:2048
	s_add_u32 s48, s44, 0xfffc0080
	s_addc_u32 s49, s45, -1
	s_and_b64 s[46:47], s[46:47], exec
	s_cselect_b32 s49, s27, s49
	s_cselect_b32 s48, s68, s48
	s_cselect_b32 s47, s69, s74
	s_cselect_b32 s46, s70, s71
	v_lshl_add_u64 v[154:155], s[44:45], 0, v[138:139]
	s_add_i32 m0, s55, 0xc000
	ds_read_b128 v[194:197], v150
	v_xor_b32_e32 v253, 64, v150
	ds_read_b128 v[198:201], v253
	ds_read_b128 v[202:205], v150 offset:2048
	ds_read_b128 v[206:209], v253 offset:2048
	ds_read_b128 v[210:213], v150 offset:4096
	ds_read_b128 v[214:217], v253 offset:4096
	ds_read_b128 v[218:221], v150 offset:6144
	ds_read_b128 v[222:225], v253 offset:6144
	global_load_lds_dwordx4 v[154:155], off
	v_lshl_add_u64 v[154:155], s[44:45], 0, v[136:137]
	s_add_i32 m0, s55, 0xe000
	s_nop 0
	global_load_lds_dwordx4 v[154:155], off
	s_waitcnt vmcnt(12)
	s_waitcnt lgkmcnt(0)
	s_barrier
	s_setprio 1
	s_waitcnt lgkmcnt(0)
	v_mfma_f32_16x16x32_bf16 v[124:127], v[160:163], v[194:197], 0
	v_mfma_f32_16x16x32_bf16 v[116:119], v[168:171], v[194:197], 0
	v_mfma_f32_16x16x32_bf16 v[108:111], v[160:163], v[202:205], 0
	v_mfma_f32_16x16x32_bf16 v[100:103], v[168:171], v[202:205], 0
	v_mfma_f32_16x16x32_bf16 v[92:95], v[160:163], v[210:213], 0
	v_mfma_f32_16x16x32_bf16 v[84:87], v[168:171], v[210:213], 0
	v_mfma_f32_16x16x32_bf16 v[76:79], v[160:163], v[218:221], 0
	v_mfma_f32_16x16x32_bf16 v[68:71], v[168:171], v[218:221], 0
	v_mfma_f32_16x16x32_bf16 v[124:127], v[164:167], v[198:201], v[124:127]
	v_mfma_f32_16x16x32_bf16 v[116:119], v[172:175], v[198:201], v[116:119]
	v_mfma_f32_16x16x32_bf16 v[108:111], v[164:167], v[206:209], v[108:111]
	v_mfma_f32_16x16x32_bf16 v[100:103], v[172:175], v[206:209], v[100:103]
	v_mfma_f32_16x16x32_bf16 v[92:95], v[164:167], v[214:217], v[92:95]
	v_mfma_f32_16x16x32_bf16 v[84:87], v[172:175], v[214:217], v[84:87]
	v_mfma_f32_16x16x32_bf16 v[76:79], v[164:167], v[222:225], v[76:79]
	v_mfma_f32_16x16x32_bf16 v[68:71], v[172:175], v[222:225], v[68:71]
	s_setprio 0
	s_setprio 1
	v_mfma_f32_16x16x32_bf16 v[120:123], v[176:179], v[194:197], 0
	v_mfma_f32_16x16x32_bf16 v[112:115], v[186:189], v[194:197], 0
	v_mfma_f32_16x16x32_bf16 v[104:107], v[176:179], v[202:205], 0
	v_mfma_f32_16x16x32_bf16 v[96:99], v[186:189], v[202:205], 0
	v_mfma_f32_16x16x32_bf16 v[88:91], v[176:179], v[210:213], 0
	v_mfma_f32_16x16x32_bf16 v[80:83], v[186:189], v[210:213], 0
	v_mfma_f32_16x16x32_bf16 v[72:75], v[176:179], v[218:221], 0
	v_mfma_f32_16x16x32_bf16 v[64:67], v[186:189], v[218:221], 0
	v_mfma_f32_16x16x32_bf16 v[120:123], v[180:183], v[198:201], v[120:123]
	v_mfma_f32_16x16x32_bf16 v[112:115], v[190:193], v[198:201], v[112:115]
	v_mfma_f32_16x16x32_bf16 v[104:107], v[180:183], v[206:209], v[104:107]
	v_mfma_f32_16x16x32_bf16 v[96:99], v[190:193], v[206:209], v[96:99]
	v_mfma_f32_16x16x32_bf16 v[88:91], v[180:183], v[214:217], v[88:91]
	v_mfma_f32_16x16x32_bf16 v[80:83], v[190:193], v[214:217], v[80:83]
	v_mfma_f32_16x16x32_bf16 v[72:75], v[180:183], v[222:225], v[72:75]
	v_mfma_f32_16x16x32_bf16 v[64:67], v[190:193], v[222:225], v[64:67]
	s_setprio 0
	s_barrier
	v_add_u32_e32 v235, 0x84000, v235
	v_add_u32_e32 v234, 0x21800, v151
	ds_read_b128 v[236:239], v234
	ds_read_b128 v[240:243], v234 offset:256
	ds_read_b128 v[244:247], v234 offset:512
	ds_read_b128 v[248:251], v234 offset:768
	s_add_i32 s76, s64, s52
	v_lshl_add_u64 v[154:155], s[46:47], 0, v[132:133]
	s_mov_b32 m0, s76
	ds_read_b128 v[194:197], v150 offset:16384
	v_xor_b32_e32 v253, 64, v150
	ds_read_b128 v[198:201], v253 offset:16384
	ds_read_b128 v[202:205], v150 offset:18432
	ds_read_b128 v[206:209], v253 offset:18432
	ds_read_b128 v[210:213], v150 offset:20480
	ds_read_b128 v[214:217], v253 offset:20480
	ds_read_b128 v[218:221], v150 offset:22528
	ds_read_b128 v[222:225], v253 offset:22528
	global_load_lds_dwordx4 v[154:155], off
	s_add_i32 m0, s76, 0x2000
	s_add_u32 s76, s46, 0x40000
	v_lshl_add_u64 v[226:227], s[46:47], 0, v[128:129]
	s_addc_u32 s77, s47, 0
	s_add_i32 s78, s65, s52
	global_load_lds_dwordx4 v[226:227], off
	v_lshl_add_u64 v[228:229], s[76:77], 0, v[132:133]
	s_mov_b32 m0, s78
	v_lshl_add_u64 v[230:231], s[48:49], 0, v[130:131]
	global_load_lds_dwordx4 v[228:229], off
	v_lshl_add_u64 v[228:229], s[76:77], 0, v[128:129]
	s_add_i32 m0, s78, 0x2000
	s_nop 0
	global_load_lds_dwordx4 v[228:229], off
	v_lshl_add_u64 v[228:229], s[48:49], 0, v[134:135]
	s_mov_b32 m0, s55
	s_nop 0
	global_load_lds_dwordx4 v[228:229], off
	s_mov_b32 m0, s56
	s_nop 0
	global_load_lds_dwordx4 v[230:231], off
	s_waitcnt lgkmcnt(8)
	v_add_f32_e32 v236, v236, v237
	v_add_f32_e32 v238, v238, v239
	v_add_f32_e32 v240, v240, v241
	v_add_f32_e32 v242, v242, v243
	v_add_f32_e32 v244, v244, v245
	v_add_f32_e32 v246, v246, v247
	v_add_f32_e32 v248, v248, v249
	v_add_f32_e32 v250, v250, v251
	v_add_f32_e32 v236, v236, v238
	v_add_f32_e32 v240, v240, v242
	v_add_f32_e32 v244, v244, v246
	v_add_f32_e32 v248, v248, v250
	v_fmamk_f32 v236, v236, 0x3a800000, v152
	v_fmamk_f32 v240, v240, 0x3a800000, v152
	v_fmamk_f32 v244, v244, 0x3a800000, v152
	v_fmamk_f32 v248, v248, 0x3a800000, v152
	v_rsq_f32_e32 v236, v236
	v_rsq_f32_e32 v240, v240
	v_rsq_f32_e32 v244, v244
	v_rsq_f32_e32 v248, v248
	v_mul_f32_e32 v252, 0xbfb8aa3b, v236
	v_mul_f32_e32 v254, v236, v236
	v_rcp_f32_e32 v254, v254
	v_pk_mul_f32 v[56:57], v[60:61], v[56:57]
	v_pk_mul_f32 v[58:59], v[62:63], v[58:59]
	v_pk_mul_f32 v[48:49], v[52:53], v[48:49]
	v_pk_mul_f32 v[50:51], v[54:55], v[50:51]
	v_pk_mul_f32 v[60:61], v[60:61], v[252:253] op_sel_hi:[1,0]
	v_pk_mul_f32 v[62:63], v[62:63], v[252:253] op_sel_hi:[1,0]
	v_pk_mul_f32 v[52:53], v[52:53], v[252:253] op_sel_hi:[1,0]
	v_pk_mul_f32 v[54:55], v[54:55], v[252:253] op_sel_hi:[1,0]
	v_exp_f32_e32 v60, v60
	v_exp_f32_e32 v61, v61
	v_exp_f32_e32 v62, v62
	v_exp_f32_e32 v63, v63
	v_exp_f32_e32 v52, v52
	v_exp_f32_e32 v53, v53
	v_exp_f32_e32 v54, v54
	v_exp_f32_e32 v55, v55
	v_pk_fma_f32 v[60:61], v[60:61], v[254:255], v[254:255] op_sel_hi:[1,0,0]
	v_pk_fma_f32 v[62:63], v[62:63], v[254:255], v[254:255] op_sel_hi:[1,0,0]
	v_pk_fma_f32 v[52:53], v[52:53], v[254:255], v[254:255] op_sel_hi:[1,0,0]
	v_pk_fma_f32 v[54:55], v[54:55], v[254:255], v[254:255] op_sel_hi:[1,0,0]
	v_rcp_f32_e32 v60, v60
	v_rcp_f32_e32 v61, v61
	v_rcp_f32_e32 v62, v62
	v_rcp_f32_e32 v63, v63
	v_rcp_f32_e32 v52, v52
	v_rcp_f32_e32 v53, v53
	v_rcp_f32_e32 v54, v54
	v_rcp_f32_e32 v55, v55
	v_pk_mul_f32 v[56:57], v[56:57], v[60:61]
	v_pk_mul_f32 v[58:59], v[58:59], v[62:63]
	v_pk_mul_f32 v[48:49], v[48:49], v[52:53]
	v_pk_mul_f32 v[50:51], v[50:51], v[54:55]
	v_cvt_pk_bf16_f32 v56, v56, v57
	v_cvt_pk_bf16_f32 v57, v58, v59
	v_cvt_pk_bf16_f32 v58, v48, v49
	v_cvt_pk_bf16_f32 v59, v50, v51
	global_store_dwordx4 v235, v[56:59], s[10:11]
	v_add_u32_e32 v234, 0x16000, v235
	v_mul_f32_e32 v252, 0xbfb8aa3b, v240
	v_mul_f32_e32 v254, v240, v240
	v_rcp_f32_e32 v254, v254
	v_pk_mul_f32 v[40:41], v[44:45], v[40:41]
	v_pk_mul_f32 v[42:43], v[46:47], v[42:43]
	v_pk_mul_f32 v[32:33], v[36:37], v[32:33]
	v_pk_mul_f32 v[34:35], v[38:39], v[34:35]
	v_pk_mul_f32 v[44:45], v[44:45], v[252:253] op_sel_hi:[1,0]
	v_pk_mul_f32 v[46:47], v[46:47], v[252:253] op_sel_hi:[1,0]
	v_pk_mul_f32 v[36:37], v[36:37], v[252:253] op_sel_hi:[1,0]
	v_pk_mul_f32 v[38:39], v[38:39], v[252:253] op_sel_hi:[1,0]
	v_exp_f32_e32 v44, v44
	v_exp_f32_e32 v45, v45
	v_exp_f32_e32 v46, v46
	v_exp_f32_e32 v47, v47
	v_exp_f32_e32 v36, v36
	v_exp_f32_e32 v37, v37
	v_exp_f32_e32 v38, v38
	v_exp_f32_e32 v39, v39
	v_pk_fma_f32 v[44:45], v[44:45], v[254:255], v[254:255] op_sel_hi:[1,0,0]
	v_pk_fma_f32 v[46:47], v[46:47], v[254:255], v[254:255] op_sel_hi:[1,0,0]
	v_pk_fma_f32 v[36:37], v[36:37], v[254:255], v[254:255] op_sel_hi:[1,0,0]
	v_pk_fma_f32 v[38:39], v[38:39], v[254:255], v[254:255] op_sel_hi:[1,0,0]
	v_rcp_f32_e32 v44, v44
	v_rcp_f32_e32 v45, v45
	v_rcp_f32_e32 v46, v46
	v_rcp_f32_e32 v47, v47
	v_rcp_f32_e32 v36, v36
	v_rcp_f32_e32 v37, v37
	v_rcp_f32_e32 v38, v38
	v_rcp_f32_e32 v39, v39
	v_pk_mul_f32 v[40:41], v[40:41], v[44:45]
	v_pk_mul_f32 v[42:43], v[42:43], v[46:47]
	v_pk_mul_f32 v[32:33], v[32:33], v[36:37]
	v_pk_mul_f32 v[34:35], v[34:35], v[38:39]
	v_cvt_pk_bf16_f32 v40, v40, v41
	v_cvt_pk_bf16_f32 v41, v42, v43
	v_cvt_pk_bf16_f32 v42, v32, v33
	v_cvt_pk_bf16_f32 v43, v34, v35
	global_store_dwordx4 v234, v[40:43], s[10:11]
	v_add_u32_e32 v235, 0x16000, v234
	v_mul_f32_e32 v252, 0xbfb8aa3b, v244
	v_mul_f32_e32 v254, v244, v244
	v_rcp_f32_e32 v254, v254
	v_pk_mul_f32 v[24:25], v[28:29], v[24:25]
	v_pk_mul_f32 v[26:27], v[30:31], v[26:27]
	v_pk_mul_f32 v[16:17], v[20:21], v[16:17]
	v_pk_mul_f32 v[18:19], v[22:23], v[18:19]
	v_pk_mul_f32 v[28:29], v[28:29], v[252:253] op_sel_hi:[1,0]
	v_pk_mul_f32 v[30:31], v[30:31], v[252:253] op_sel_hi:[1,0]
	v_pk_mul_f32 v[20:21], v[20:21], v[252:253] op_sel_hi:[1,0]
	v_pk_mul_f32 v[22:23], v[22:23], v[252:253] op_sel_hi:[1,0]
	v_exp_f32_e32 v28, v28
	v_exp_f32_e32 v29, v29
	v_exp_f32_e32 v30, v30
	v_exp_f32_e32 v31, v31
	v_exp_f32_e32 v20, v20
	v_exp_f32_e32 v21, v21
	v_exp_f32_e32 v22, v22
	v_exp_f32_e32 v23, v23
	v_pk_fma_f32 v[28:29], v[28:29], v[254:255], v[254:255] op_sel_hi:[1,0,0]
	v_pk_fma_f32 v[30:31], v[30:31], v[254:255], v[254:255] op_sel_hi:[1,0,0]
	v_pk_fma_f32 v[20:21], v[20:21], v[254:255], v[254:255] op_sel_hi:[1,0,0]
	v_pk_fma_f32 v[22:23], v[22:23], v[254:255], v[254:255] op_sel_hi:[1,0,0]
	v_rcp_f32_e32 v28, v28
	v_rcp_f32_e32 v29, v29
	v_rcp_f32_e32 v30, v30
	v_rcp_f32_e32 v31, v31
	v_rcp_f32_e32 v20, v20
	v_rcp_f32_e32 v21, v21
	v_rcp_f32_e32 v22, v22
	v_rcp_f32_e32 v23, v23
	v_pk_mul_f32 v[24:25], v[24:25], v[28:29]
	v_pk_mul_f32 v[26:27], v[26:27], v[30:31]
	v_pk_mul_f32 v[16:17], v[16:17], v[20:21]
	v_pk_mul_f32 v[18:19], v[18:19], v[22:23]
	v_cvt_pk_bf16_f32 v24, v24, v25
	v_cvt_pk_bf16_f32 v25, v26, v27
	v_cvt_pk_bf16_f32 v26, v16, v17
	v_cvt_pk_bf16_f32 v27, v18, v19
	global_store_dwordx4 v235, v[24:27], s[10:11]
	v_add_u32_e32 v234, 0x16000, v235
	v_mul_f32_e32 v252, 0xbfb8aa3b, v248
	v_mul_f32_e32 v254, v248, v248
	v_rcp_f32_e32 v254, v254
	v_pk_mul_f32 v[8:9], v[12:13], v[8:9]
	v_pk_mul_f32 v[10:11], v[14:15], v[10:11]
	v_pk_mul_f32 v[0:1], v[4:5], v[0:1]
	v_pk_mul_f32 v[2:3], v[6:7], v[2:3]
	v_pk_mul_f32 v[12:13], v[12:13], v[252:253] op_sel_hi:[1,0]
	v_pk_mul_f32 v[14:15], v[14:15], v[252:253] op_sel_hi:[1,0]
	v_pk_mul_f32 v[4:5], v[4:5], v[252:253] op_sel_hi:[1,0]
	v_pk_mul_f32 v[6:7], v[6:7], v[252:253] op_sel_hi:[1,0]
	v_exp_f32_e32 v12, v12
	v_exp_f32_e32 v13, v13
	v_exp_f32_e32 v14, v14
	v_exp_f32_e32 v15, v15
	v_exp_f32_e32 v4, v4
	v_exp_f32_e32 v5, v5
	v_exp_f32_e32 v6, v6
	v_exp_f32_e32 v7, v7
	v_pk_fma_f32 v[12:13], v[12:13], v[254:255], v[254:255] op_sel_hi:[1,0,0]
	v_pk_fma_f32 v[14:15], v[14:15], v[254:255], v[254:255] op_sel_hi:[1,0,0]
	v_pk_fma_f32 v[4:5], v[4:5], v[254:255], v[254:255] op_sel_hi:[1,0,0]
	v_pk_fma_f32 v[6:7], v[6:7], v[254:255], v[254:255] op_sel_hi:[1,0,0]
	v_rcp_f32_e32 v12, v12
	v_rcp_f32_e32 v13, v13
	v_rcp_f32_e32 v14, v14
	v_rcp_f32_e32 v15, v15
	v_rcp_f32_e32 v4, v4
	v_rcp_f32_e32 v5, v5
	v_rcp_f32_e32 v6, v6
	v_rcp_f32_e32 v7, v7
	v_pk_mul_f32 v[8:9], v[8:9], v[12:13]
	v_pk_mul_f32 v[10:11], v[10:11], v[14:15]
	v_pk_mul_f32 v[0:1], v[0:1], v[4:5]
	v_pk_mul_f32 v[2:3], v[2:3], v[6:7]
	v_cvt_pk_bf16_f32 v8, v8, v9
	v_cvt_pk_bf16_f32 v9, v10, v11
	v_cvt_pk_bf16_f32 v10, v0, v1
	v_cvt_pk_bf16_f32 v11, v2, v3
	global_store_dwordx4 v234, v[8:11], s[10:11]
	s_waitcnt vmcnt(16)
	s_waitcnt lgkmcnt(0)
	s_barrier
	s_setprio 1
	s_waitcnt lgkmcnt(0)
	v_mfma_f32_16x16x32_bf16 v[60:63], v[160:163], v[194:197], 0
	v_mfma_f32_16x16x32_bf16 v[52:55], v[168:171], v[194:197], 0
	v_mfma_f32_16x16x32_bf16 v[44:47], v[160:163], v[202:205], 0
	v_mfma_f32_16x16x32_bf16 v[36:39], v[168:171], v[202:205], 0
	v_mfma_f32_16x16x32_bf16 v[28:31], v[160:163], v[210:213], 0
	v_mfma_f32_16x16x32_bf16 v[20:23], v[168:171], v[210:213], 0
	v_mfma_f32_16x16x32_bf16 v[12:15], v[160:163], v[218:221], 0
	v_mfma_f32_16x16x32_bf16 v[4:7], v[168:171], v[218:221], 0
	v_mfma_f32_16x16x32_bf16 v[60:63], v[164:167], v[198:201], v[60:63]
	v_mfma_f32_16x16x32_bf16 v[52:55], v[172:175], v[198:201], v[52:55]
	v_mfma_f32_16x16x32_bf16 v[44:47], v[164:167], v[206:209], v[44:47]
	v_mfma_f32_16x16x32_bf16 v[36:39], v[172:175], v[206:209], v[36:39]
	v_mfma_f32_16x16x32_bf16 v[28:31], v[164:167], v[214:217], v[28:31]
	v_mfma_f32_16x16x32_bf16 v[20:23], v[172:175], v[214:217], v[20:23]
	v_mfma_f32_16x16x32_bf16 v[12:15], v[164:167], v[222:225], v[12:15]
	v_mfma_f32_16x16x32_bf16 v[4:7], v[172:175], v[222:225], v[4:7]
	s_setprio 0
	s_setprio 1
	v_mfma_f32_16x16x32_bf16 v[56:59], v[176:179], v[194:197], 0
	v_mfma_f32_16x16x32_bf16 v[48:51], v[186:189], v[194:197], 0
	v_mfma_f32_16x16x32_bf16 v[40:43], v[176:179], v[202:205], 0
	v_mfma_f32_16x16x32_bf16 v[32:35], v[186:189], v[202:205], 0
	v_mfma_f32_16x16x32_bf16 v[24:27], v[176:179], v[210:213], 0
	v_mfma_f32_16x16x32_bf16 v[16:19], v[186:189], v[210:213], 0
	v_mfma_f32_16x16x32_bf16 v[8:11], v[176:179], v[218:221], 0
	v_mfma_f32_16x16x32_bf16 v[0:3], v[186:189], v[218:221], 0
	v_mfma_f32_16x16x32_bf16 v[56:59], v[180:183], v[198:201], v[56:59]
	v_mfma_f32_16x16x32_bf16 v[48:51], v[190:193], v[198:201], v[48:51]
	v_mfma_f32_16x16x32_bf16 v[40:43], v[180:183], v[206:209], v[40:43]
	v_mfma_f32_16x16x32_bf16 v[32:35], v[190:193], v[206:209], v[32:35]
	v_mfma_f32_16x16x32_bf16 v[24:27], v[180:183], v[214:217], v[24:27]
	v_mfma_f32_16x16x32_bf16 v[16:19], v[190:193], v[214:217], v[16:19]
	v_mfma_f32_16x16x32_bf16 v[8:11], v[180:183], v[222:225], v[8:11]
	v_mfma_f32_16x16x32_bf16 v[0:3], v[190:193], v[222:225], v[0:3]
	s_setprio 0
	s_barrier
	s_add_i32 s76, 0, 0x18000
	v_add_u32_e32 v153, s76, v147
	s_add_i32 s77, 0, 0x1c000
	ds_read_b128 v[160:163], v153
	v_xor_b32_e32 v253, 64, v153
	ds_read_b128 v[164:167], v253
	ds_read_b128 v[168:171], v153 offset:2048
	ds_read_b128 v[172:175], v253 offset:2048
	v_add_u32_e32 v153, s77, v147
	ds_read_b128 v[176:179], v153
	v_xor_b32_e32 v253, 64, v153
	ds_read_b128 v[180:183], v253
	ds_read_b128 v[186:189], v153 offset:2048
	ds_read_b128 v[190:193], v253 offset:2048
	s_add_u32 s48, s48, 0x40000
	s_addc_u32 s49, s49, 0
	s_mov_b32 m0, s57
	v_lshl_add_u64 v[232:233], s[48:49], 0, v[134:135]
	ds_read_b128 v[194:197], v150 offset:32768
	v_xor_b32_e32 v253, 64, v150
	ds_read_b128 v[198:201], v253 offset:32768
	ds_read_b128 v[202:205], v150 offset:34816
	ds_read_b128 v[206:209], v253 offset:34816
	ds_read_b128 v[210:213], v150 offset:36864
	ds_read_b128 v[214:217], v253 offset:36864
	ds_read_b128 v[218:221], v150 offset:38912
	ds_read_b128 v[222:225], v253 offset:38912
	global_load_lds_dwordx4 v[232:233], off
	v_lshl_add_u64 v[232:233], s[48:49], 0, v[130:131]
	s_mov_b32 m0, s58
	s_nop 0
	global_load_lds_dwordx4 v[232:233], off
	s_waitcnt vmcnt(12)
	s_waitcnt lgkmcnt(0)
	s_barrier
	s_setprio 1
	s_waitcnt lgkmcnt(0)
	v_mfma_f32_16x16x32_bf16 v[124:127], v[160:163], v[194:197], v[124:127]
	v_mfma_f32_16x16x32_bf16 v[124:127], v[164:167], v[198:201], v[124:127]
	v_mfma_f32_16x16x32_bf16 v[116:119], v[172:175], v[198:201], v[116:119]
	v_mfma_f32_16x16x32_bf16 v[116:119], v[168:171], v[194:197], v[116:119]
	v_mfma_f32_16x16x32_bf16 v[100:103], v[168:171], v[202:205], v[100:103]
	v_mfma_f32_16x16x32_bf16 v[100:103], v[172:175], v[206:209], v[100:103]
	v_mfma_f32_16x16x32_bf16 v[108:111], v[164:167], v[206:209], v[108:111]
	v_mfma_f32_16x16x32_bf16 v[108:111], v[160:163], v[202:205], v[108:111]
	v_mfma_f32_16x16x32_bf16 v[92:95], v[160:163], v[210:213], v[92:95]
	v_mfma_f32_16x16x32_bf16 v[92:95], v[164:167], v[214:217], v[92:95]
	v_mfma_f32_16x16x32_bf16 v[84:87], v[172:175], v[214:217], v[84:87]
	v_mfma_f32_16x16x32_bf16 v[84:87], v[168:171], v[210:213], v[84:87]
	v_mfma_f32_16x16x32_bf16 v[68:71], v[168:171], v[218:221], v[68:71]
	v_mfma_f32_16x16x32_bf16 v[68:71], v[172:175], v[222:225], v[68:71]
	v_mfma_f32_16x16x32_bf16 v[76:79], v[164:167], v[222:225], v[76:79]
	v_mfma_f32_16x16x32_bf16 v[76:79], v[160:163], v[218:221], v[76:79]
	s_setprio 0
	s_setprio 1
	v_mfma_f32_16x16x32_bf16 v[120:123], v[176:179], v[194:197], v[120:123]
	v_mfma_f32_16x16x32_bf16 v[120:123], v[180:183], v[198:201], v[120:123]
	v_mfma_f32_16x16x32_bf16 v[112:115], v[190:193], v[198:201], v[112:115]
	v_mfma_f32_16x16x32_bf16 v[112:115], v[186:189], v[194:197], v[112:115]
	v_mfma_f32_16x16x32_bf16 v[96:99], v[186:189], v[202:205], v[96:99]
	v_mfma_f32_16x16x32_bf16 v[96:99], v[190:193], v[206:209], v[96:99]
	v_mfma_f32_16x16x32_bf16 v[104:107], v[180:183], v[206:209], v[104:107]
	v_mfma_f32_16x16x32_bf16 v[104:107], v[176:179], v[202:205], v[104:107]
	v_mfma_f32_16x16x32_bf16 v[88:91], v[176:179], v[210:213], v[88:91]
	v_mfma_f32_16x16x32_bf16 v[88:91], v[180:183], v[214:217], v[88:91]
	v_mfma_f32_16x16x32_bf16 v[80:83], v[190:193], v[214:217], v[80:83]
	v_mfma_f32_16x16x32_bf16 v[80:83], v[186:189], v[210:213], v[80:83]
	v_mfma_f32_16x16x32_bf16 v[64:67], v[186:189], v[218:221], v[64:67]
	v_mfma_f32_16x16x32_bf16 v[64:67], v[190:193], v[222:225], v[64:67]
	v_mfma_f32_16x16x32_bf16 v[72:75], v[180:183], v[222:225], v[72:75]
	v_mfma_f32_16x16x32_bf16 v[72:75], v[176:179], v[218:221], v[72:75]
	s_setprio 0
	s_barrier
	s_add_i32 s48, s76, s52
	v_lshl_add_u64 v[154:155], v[154:155], 0, s[14:15]
	s_mov_b32 m0, s48
	ds_read_b128 v[194:197], v150 offset:49152
	v_xor_b32_e32 v253, 64, v150
	ds_read_b128 v[198:201], v253 offset:49152
	ds_read_b128 v[202:205], v150 offset:51200
	ds_read_b128 v[206:209], v253 offset:51200
	ds_read_b128 v[210:213], v150 offset:53248
	ds_read_b128 v[214:217], v253 offset:53248
	ds_read_b128 v[218:221], v150 offset:55296
	ds_read_b128 v[222:225], v253 offset:55296
	global_load_lds_dwordx4 v[154:155], off
	s_add_i32 m0, s48, 0x2000
	s_add_u32 s46, s46, 0x40080
	v_lshl_add_u64 v[154:155], v[226:227], 0, s[14:15]
	s_addc_u32 s47, s47, 0
	s_add_i32 s48, s77, s52
	global_load_lds_dwordx4 v[154:155], off
	v_lshl_add_u64 v[154:155], s[46:47], 0, v[132:133]
	s_mov_b32 m0, s48
	s_nop 0
	global_load_lds_dwordx4 v[154:155], off
	v_lshl_add_u64 v[154:155], s[46:47], 0, v[128:129]
	s_add_i32 m0, s48, 0x2000
	s_nop 0
	global_load_lds_dwordx4 v[154:155], off
	v_lshl_add_u64 v[154:155], v[228:229], 0, s[14:15]
	s_mov_b32 m0, s60
	s_nop 0
	global_load_lds_dwordx4 v[154:155], off
	v_lshl_add_u64 v[154:155], v[230:231], 0, s[14:15]
	s_mov_b32 m0, s61
	s_nop 0
	global_load_lds_dwordx4 v[154:155], off
	s_waitcnt vmcnt(8)
	s_waitcnt lgkmcnt(0)
	s_barrier
	s_setprio 1
	s_waitcnt lgkmcnt(0)
	v_mfma_f32_16x16x32_bf16 v[60:63], v[160:163], v[194:197], v[60:63]
	v_mfma_f32_16x16x32_bf16 v[60:63], v[164:167], v[198:201], v[60:63]
	v_mfma_f32_16x16x32_bf16 v[52:55], v[172:175], v[198:201], v[52:55]
	v_mfma_f32_16x16x32_bf16 v[52:55], v[168:171], v[194:197], v[52:55]
	v_mfma_f32_16x16x32_bf16 v[36:39], v[168:171], v[202:205], v[36:39]
	v_mfma_f32_16x16x32_bf16 v[36:39], v[172:175], v[206:209], v[36:39]
	v_mfma_f32_16x16x32_bf16 v[44:47], v[164:167], v[206:209], v[44:47]
	v_mfma_f32_16x16x32_bf16 v[44:47], v[160:163], v[202:205], v[44:47]
	v_mfma_f32_16x16x32_bf16 v[28:31], v[160:163], v[210:213], v[28:31]
	v_mfma_f32_16x16x32_bf16 v[28:31], v[164:167], v[214:217], v[28:31]
	v_mfma_f32_16x16x32_bf16 v[20:23], v[172:175], v[214:217], v[20:23]
	v_mfma_f32_16x16x32_bf16 v[20:23], v[168:171], v[210:213], v[20:23]
	v_mfma_f32_16x16x32_bf16 v[4:7], v[168:171], v[218:221], v[4:7]
	v_mfma_f32_16x16x32_bf16 v[4:7], v[172:175], v[222:225], v[4:7]
	v_mfma_f32_16x16x32_bf16 v[12:15], v[164:167], v[222:225], v[12:15]
	v_mfma_f32_16x16x32_bf16 v[12:15], v[160:163], v[218:221], v[12:15]
	s_setprio 0
	s_setprio 1
	v_mfma_f32_16x16x32_bf16 v[56:59], v[176:179], v[194:197], v[56:59]
	v_mfma_f32_16x16x32_bf16 v[56:59], v[180:183], v[198:201], v[56:59]
	v_mfma_f32_16x16x32_bf16 v[48:51], v[190:193], v[198:201], v[48:51]
	v_mfma_f32_16x16x32_bf16 v[48:51], v[186:189], v[194:197], v[48:51]
	v_mfma_f32_16x16x32_bf16 v[32:35], v[186:189], v[202:205], v[32:35]
	v_mfma_f32_16x16x32_bf16 v[32:35], v[190:193], v[206:209], v[32:35]
	v_mfma_f32_16x16x32_bf16 v[40:43], v[180:183], v[206:209], v[40:43]
	v_mfma_f32_16x16x32_bf16 v[40:43], v[176:179], v[202:205], v[40:43]
	v_mfma_f32_16x16x32_bf16 v[24:27], v[176:179], v[210:213], v[24:27]
	v_mfma_f32_16x16x32_bf16 v[24:27], v[180:183], v[214:217], v[24:27]
	v_mfma_f32_16x16x32_bf16 v[16:19], v[190:193], v[214:217], v[16:19]
	v_mfma_f32_16x16x32_bf16 v[16:19], v[186:189], v[210:213], v[16:19]
	v_mfma_f32_16x16x32_bf16 v[0:3], v[186:189], v[218:221], v[0:3]
	v_mfma_f32_16x16x32_bf16 v[0:3], v[190:193], v[222:225], v[0:3]
	v_mfma_f32_16x16x32_bf16 v[8:11], v[180:183], v[222:225], v[8:11]
	v_mfma_f32_16x16x32_bf16 v[8:11], v[176:179], v[218:221], v[8:11]
	s_setprio 0
	s_barrier
	s_add_i32 s75, s75, 2
	s_add_u32 s71, s71, 0x100
	s_addc_u32 s74, s74, 0
	s_add_u32 s44, s44, 0x100
	s_addc_u32 s45, s45, 0
	s_branch .LBB0_76

.LBB0_525:
	s_ashr_i32 s29, s28, 31
	s_lshl_b64 s[30:31], s[28:29], 19
	s_add_u32 s30, s3, s30
	s_addc_u32 s31, s35, s31
	s_and_b64 s[44:45], s[10:11], exec
	s_cselect_b32 s29, s31, s51
	s_cselect_b32 s70, s30, s50
	s_ashr_i32 s27, s26, 31
	s_lshl_b64 s[44:45], s[26:27], 19
	s_add_u32 s44, s52, s44
	s_addc_u32 s45, s53, s45
	s_and_b64 s[72:73], s[10:11], exec
	s_cselect_b32 s71, s45, s49
	s_cselect_b32 s72, s44, s48
	s_lshl_b32 s27, s46, 8
	v_add_u32_e32 v250, s27, v148
	s_add_u32 s73, s48, 0x100
	v_ashrrev_i32_e32 v251, 31, v250
	s_addc_u32 s74, s49, 0
	v_lshl_add_u64 v[144:145], v[250:251], 4, s[16:17]
	s_add_u32 s46, s50, 0x40080
	s_addc_u32 s47, s51, 0
	s_mov_b32 s75, -2
	s_mov_b64 s[48:49], 0
	s_cmp_eq_u32 s61, 1
	s_cbranch_scc1 .Lfa_4
	v_add_u32_e32 v153, s66, v147
	ds_read_b128 v[160:163], v153
	v_xor_b32_e32 v253, 64, v153
	ds_read_b128 v[164:167], v253
	ds_read_b128 v[168:171], v153 offset:2048
	ds_read_b128 v[172:175], v253 offset:2048
	v_add_u32_e32 v153, s67, v147
	ds_read_b128 v[176:179], v153
	v_xor_b32_e32 v253, 64, v153
	ds_read_b128 v[180:183], v253
	ds_read_b128 v[186:189], v153 offset:2048
	ds_read_b128 v[190:193], v253 offset:2048
	s_add_u32 s50, s46, 0xfffc0080
	s_addc_u32 s51, s47, -1
	s_and_b64 s[48:49], s[48:49], exec
	s_cselect_b32 s51, s29, s51
	s_cselect_b32 s50, s70, s50
	s_cselect_b32 s49, s71, s74
	s_cselect_b32 s48, s72, s73
	v_lshl_add_u64 v[154:155], s[46:47], 0, v[138:139]
	s_add_i32 m0, s57, 0xc000
	ds_read_b128 v[194:197], v150
	v_xor_b32_e32 v253, 64, v150
	ds_read_b128 v[198:201], v253
	ds_read_b128 v[202:205], v150 offset:2048
	ds_read_b128 v[206:209], v253 offset:2048
	ds_read_b128 v[210:213], v150 offset:4096
	ds_read_b128 v[214:217], v253 offset:4096
	ds_read_b128 v[218:221], v150 offset:6144
	ds_read_b128 v[222:225], v253 offset:6144
	global_load_lds_dwordx4 v[154:155], off
	v_lshl_add_u64 v[154:155], s[46:47], 0, v[136:137]
	s_add_i32 m0, s57, 0xe000
	s_nop 0
	global_load_lds_dwordx4 v[154:155], off
	s_waitcnt vmcnt(12)
	s_waitcnt lgkmcnt(0)
	s_barrier
	s_setprio 1
	s_waitcnt lgkmcnt(0)
	v_mfma_f32_16x16x32_bf16 v[124:127], v[160:163], v[194:197], 0
	v_mfma_f32_16x16x32_bf16 v[116:119], v[168:171], v[194:197], 0
	v_mfma_f32_16x16x32_bf16 v[108:111], v[160:163], v[202:205], 0
	v_mfma_f32_16x16x32_bf16 v[100:103], v[168:171], v[202:205], 0
	v_mfma_f32_16x16x32_bf16 v[92:95], v[160:163], v[210:213], 0
	v_mfma_f32_16x16x32_bf16 v[84:87], v[168:171], v[210:213], 0
	v_mfma_f32_16x16x32_bf16 v[76:79], v[160:163], v[218:221], 0
	v_mfma_f32_16x16x32_bf16 v[68:71], v[168:171], v[218:221], 0
	v_mfma_f32_16x16x32_bf16 v[124:127], v[164:167], v[198:201], v[124:127]
	v_mfma_f32_16x16x32_bf16 v[116:119], v[172:175], v[198:201], v[116:119]
	v_mfma_f32_16x16x32_bf16 v[108:111], v[164:167], v[206:209], v[108:111]
	v_mfma_f32_16x16x32_bf16 v[100:103], v[172:175], v[206:209], v[100:103]
	v_mfma_f32_16x16x32_bf16 v[92:95], v[164:167], v[214:217], v[92:95]
	v_mfma_f32_16x16x32_bf16 v[84:87], v[172:175], v[214:217], v[84:87]
	v_mfma_f32_16x16x32_bf16 v[76:79], v[164:167], v[222:225], v[76:79]
	v_mfma_f32_16x16x32_bf16 v[68:71], v[172:175], v[222:225], v[68:71]
	s_setprio 0
	s_setprio 1
	v_mfma_f32_16x16x32_bf16 v[120:123], v[176:179], v[194:197], 0
	v_mfma_f32_16x16x32_bf16 v[112:115], v[186:189], v[194:197], 0
	v_mfma_f32_16x16x32_bf16 v[104:107], v[176:179], v[202:205], 0
	v_mfma_f32_16x16x32_bf16 v[96:99], v[186:189], v[202:205], 0
	v_mfma_f32_16x16x32_bf16 v[88:91], v[176:179], v[210:213], 0
	v_mfma_f32_16x16x32_bf16 v[80:83], v[186:189], v[210:213], 0
	v_mfma_f32_16x16x32_bf16 v[72:75], v[176:179], v[218:221], 0
	v_mfma_f32_16x16x32_bf16 v[64:67], v[186:189], v[218:221], 0
	v_mfma_f32_16x16x32_bf16 v[120:123], v[180:183], v[198:201], v[120:123]
	v_mfma_f32_16x16x32_bf16 v[112:115], v[190:193], v[198:201], v[112:115]
	v_mfma_f32_16x16x32_bf16 v[104:107], v[180:183], v[206:209], v[104:107]
	v_mfma_f32_16x16x32_bf16 v[96:99], v[190:193], v[206:209], v[96:99]
	v_mfma_f32_16x16x32_bf16 v[88:91], v[180:183], v[214:217], v[88:91]
	v_mfma_f32_16x16x32_bf16 v[80:83], v[190:193], v[214:217], v[80:83]
	v_mfma_f32_16x16x32_bf16 v[72:75], v[180:183], v[222:225], v[72:75]
	v_mfma_f32_16x16x32_bf16 v[64:67], v[190:193], v[222:225], v[64:67]
	s_setprio 0
	s_barrier
	v_add_u32_e32 v235, 0x84000, v235
	v_add_u32_e32 v234, 0x21800, v151
	ds_read_b128 v[236:239], v234
	ds_read_b128 v[240:243], v234 offset:256
	ds_read_b128 v[244:247], v234 offset:512
	ds_read_b128 v[248:251], v234 offset:768
	s_add_i32 s76, s66, s54
	v_lshl_add_u64 v[154:155], s[48:49], 0, v[132:133]
	s_mov_b32 m0, s76
	ds_read_b128 v[194:197], v150 offset:16384
	v_xor_b32_e32 v253, 64, v150
	ds_read_b128 v[198:201], v253 offset:16384
	ds_read_b128 v[202:205], v150 offset:18432
	ds_read_b128 v[206:209], v253 offset:18432
	ds_read_b128 v[210:213], v150 offset:20480
	ds_read_b128 v[214:217], v253 offset:20480
	ds_read_b128 v[218:221], v150 offset:22528
	ds_read_b128 v[222:225], v253 offset:22528
	global_load_lds_dwordx4 v[154:155], off
	s_add_i32 m0, s76, 0x2000
	s_add_u32 s76, s48, 0x40000
	v_lshl_add_u64 v[226:227], s[48:49], 0, v[128:129]
	s_addc_u32 s77, s49, 0
	s_add_i32 s78, s67, s54
	global_load_lds_dwordx4 v[226:227], off
	v_lshl_add_u64 v[228:229], s[76:77], 0, v[132:133]
	s_mov_b32 m0, s78
	v_lshl_add_u64 v[230:231], s[50:51], 0, v[130:131]
	global_load_lds_dwordx4 v[228:229], off
	v_lshl_add_u64 v[228:229], s[76:77], 0, v[128:129]
	s_add_i32 m0, s78, 0x2000
	s_nop 0
	global_load_lds_dwordx4 v[228:229], off
	v_lshl_add_u64 v[228:229], s[50:51], 0, v[134:135]
	s_mov_b32 m0, s57
	s_nop 0
	global_load_lds_dwordx4 v[228:229], off
	s_mov_b32 m0, s58
	s_nop 0
	global_load_lds_dwordx4 v[230:231], off
	s_waitcnt lgkmcnt(8)
	v_add_f32_e32 v236, v236, v237
	v_add_f32_e32 v238, v238, v239
	v_add_f32_e32 v240, v240, v241
	v_add_f32_e32 v242, v242, v243
	v_add_f32_e32 v244, v244, v245
	v_add_f32_e32 v246, v246, v247
	v_add_f32_e32 v248, v248, v249
	v_add_f32_e32 v250, v250, v251
	v_add_f32_e32 v236, v236, v238
	v_add_f32_e32 v240, v240, v242
	v_add_f32_e32 v244, v244, v246
	v_add_f32_e32 v248, v248, v250
	v_fmamk_f32 v236, v236, 0x3a800000, v152
	v_fmamk_f32 v240, v240, 0x3a800000, v152
	v_fmamk_f32 v244, v244, 0x3a800000, v152
	v_fmamk_f32 v248, v248, 0x3a800000, v152
	v_rsq_f32_e32 v236, v236
	v_rsq_f32_e32 v240, v240
	v_rsq_f32_e32 v244, v244
	v_rsq_f32_e32 v248, v248
	v_mul_f32_e32 v252, 0xbfb8aa3b, v236
	v_mul_f32_e32 v254, v236, v236
	v_rcp_f32_e32 v254, v254
	v_pk_mul_f32 v[56:57], v[60:61], v[56:57]
	v_pk_mul_f32 v[58:59], v[62:63], v[58:59]
	v_pk_mul_f32 v[48:49], v[52:53], v[48:49]
	v_pk_mul_f32 v[50:51], v[54:55], v[50:51]
	v_pk_mul_f32 v[60:61], v[60:61], v[252:253] op_sel_hi:[1,0]
	v_pk_mul_f32 v[62:63], v[62:63], v[252:253] op_sel_hi:[1,0]
	v_pk_mul_f32 v[52:53], v[52:53], v[252:253] op_sel_hi:[1,0]
	v_pk_mul_f32 v[54:55], v[54:55], v[252:253] op_sel_hi:[1,0]
	v_exp_f32_e32 v60, v60
	v_exp_f32_e32 v61, v61
	v_exp_f32_e32 v62, v62
	v_exp_f32_e32 v63, v63
	v_exp_f32_e32 v52, v52
	v_exp_f32_e32 v53, v53
	v_exp_f32_e32 v54, v54
	v_exp_f32_e32 v55, v55
	v_pk_fma_f32 v[60:61], v[60:61], v[254:255], v[254:255] op_sel_hi:[1,0,0]
	v_pk_fma_f32 v[62:63], v[62:63], v[254:255], v[254:255] op_sel_hi:[1,0,0]
	v_pk_fma_f32 v[52:53], v[52:53], v[254:255], v[254:255] op_sel_hi:[1,0,0]
	v_pk_fma_f32 v[54:55], v[54:55], v[254:255], v[254:255] op_sel_hi:[1,0,0]
	v_rcp_f32_e32 v60, v60
	v_rcp_f32_e32 v61, v61
	v_rcp_f32_e32 v62, v62
	v_rcp_f32_e32 v63, v63
	v_rcp_f32_e32 v52, v52
	v_rcp_f32_e32 v53, v53
	v_rcp_f32_e32 v54, v54
	v_rcp_f32_e32 v55, v55
	v_pk_mul_f32 v[56:57], v[56:57], v[60:61]
	v_pk_mul_f32 v[58:59], v[58:59], v[62:63]
	v_pk_mul_f32 v[48:49], v[48:49], v[52:53]
	v_pk_mul_f32 v[50:51], v[50:51], v[54:55]
	v_cvt_pk_bf16_f32 v56, v56, v57
	v_cvt_pk_bf16_f32 v57, v58, v59
	v_cvt_pk_bf16_f32 v58, v48, v49
	v_cvt_pk_bf16_f32 v59, v50, v51
	global_store_dwordx4 v235, v[56:59], s[14:15]
	v_add_u32_e32 v234, 0x16000, v235
	v_mul_f32_e32 v252, 0xbfb8aa3b, v240
	v_mul_f32_e32 v254, v240, v240
	v_rcp_f32_e32 v254, v254
	v_pk_mul_f32 v[40:41], v[44:45], v[40:41]
	v_pk_mul_f32 v[42:43], v[46:47], v[42:43]
	v_pk_mul_f32 v[32:33], v[36:37], v[32:33]
	v_pk_mul_f32 v[34:35], v[38:39], v[34:35]
	v_pk_mul_f32 v[44:45], v[44:45], v[252:253] op_sel_hi:[1,0]
	v_pk_mul_f32 v[46:47], v[46:47], v[252:253] op_sel_hi:[1,0]
	v_pk_mul_f32 v[36:37], v[36:37], v[252:253] op_sel_hi:[1,0]
	v_pk_mul_f32 v[38:39], v[38:39], v[252:253] op_sel_hi:[1,0]
	v_exp_f32_e32 v44, v44
	v_exp_f32_e32 v45, v45
	v_exp_f32_e32 v46, v46
	v_exp_f32_e32 v47, v47
	v_exp_f32_e32 v36, v36
	v_exp_f32_e32 v37, v37
	v_exp_f32_e32 v38, v38
	v_exp_f32_e32 v39, v39
	v_pk_fma_f32 v[44:45], v[44:45], v[254:255], v[254:255] op_sel_hi:[1,0,0]
	v_pk_fma_f32 v[46:47], v[46:47], v[254:255], v[254:255] op_sel_hi:[1,0,0]
	v_pk_fma_f32 v[36:37], v[36:37], v[254:255], v[254:255] op_sel_hi:[1,0,0]
	v_pk_fma_f32 v[38:39], v[38:39], v[254:255], v[254:255] op_sel_hi:[1,0,0]
	v_rcp_f32_e32 v44, v44
	v_rcp_f32_e32 v45, v45
	v_rcp_f32_e32 v46, v46
	v_rcp_f32_e32 v47, v47
	v_rcp_f32_e32 v36, v36
	v_rcp_f32_e32 v37, v37
	v_rcp_f32_e32 v38, v38
	v_rcp_f32_e32 v39, v39
	v_pk_mul_f32 v[40:41], v[40:41], v[44:45]
	v_pk_mul_f32 v[42:43], v[42:43], v[46:47]
	v_pk_mul_f32 v[32:33], v[32:33], v[36:37]
	v_pk_mul_f32 v[34:35], v[34:35], v[38:39]
	v_cvt_pk_bf16_f32 v40, v40, v41
	v_cvt_pk_bf16_f32 v41, v42, v43
	v_cvt_pk_bf16_f32 v42, v32, v33
	v_cvt_pk_bf16_f32 v43, v34, v35
	global_store_dwordx4 v234, v[40:43], s[14:15]
	v_add_u32_e32 v235, 0x16000, v234
	v_mul_f32_e32 v252, 0xbfb8aa3b, v244
	v_mul_f32_e32 v254, v244, v244
	v_rcp_f32_e32 v254, v254
	v_pk_mul_f32 v[24:25], v[28:29], v[24:25]
	v_pk_mul_f32 v[26:27], v[30:31], v[26:27]
	v_pk_mul_f32 v[16:17], v[20:21], v[16:17]
	v_pk_mul_f32 v[18:19], v[22:23], v[18:19]
	v_pk_mul_f32 v[28:29], v[28:29], v[252:253] op_sel_hi:[1,0]
	v_pk_mul_f32 v[30:31], v[30:31], v[252:253] op_sel_hi:[1,0]
	v_pk_mul_f32 v[20:21], v[20:21], v[252:253] op_sel_hi:[1,0]
	v_pk_mul_f32 v[22:23], v[22:23], v[252:253] op_sel_hi:[1,0]
	v_exp_f32_e32 v28, v28
	v_exp_f32_e32 v29, v29
	v_exp_f32_e32 v30, v30
	v_exp_f32_e32 v31, v31
	v_exp_f32_e32 v20, v20
	v_exp_f32_e32 v21, v21
	v_exp_f32_e32 v22, v22
	v_exp_f32_e32 v23, v23
	v_pk_fma_f32 v[28:29], v[28:29], v[254:255], v[254:255] op_sel_hi:[1,0,0]
	v_pk_fma_f32 v[30:31], v[30:31], v[254:255], v[254:255] op_sel_hi:[1,0,0]
	v_pk_fma_f32 v[20:21], v[20:21], v[254:255], v[254:255] op_sel_hi:[1,0,0]
	v_pk_fma_f32 v[22:23], v[22:23], v[254:255], v[254:255] op_sel_hi:[1,0,0]
	v_rcp_f32_e32 v28, v28
	v_rcp_f32_e32 v29, v29
	v_rcp_f32_e32 v30, v30
	v_rcp_f32_e32 v31, v31
	v_rcp_f32_e32 v20, v20
	v_rcp_f32_e32 v21, v21
	v_rcp_f32_e32 v22, v22
	v_rcp_f32_e32 v23, v23
	v_pk_mul_f32 v[24:25], v[24:25], v[28:29]
	v_pk_mul_f32 v[26:27], v[26:27], v[30:31]
	v_pk_mul_f32 v[16:17], v[16:17], v[20:21]
	v_pk_mul_f32 v[18:19], v[18:19], v[22:23]
	v_cvt_pk_bf16_f32 v24, v24, v25
	v_cvt_pk_bf16_f32 v25, v26, v27
	v_cvt_pk_bf16_f32 v26, v16, v17
	v_cvt_pk_bf16_f32 v27, v18, v19
	global_store_dwordx4 v235, v[24:27], s[14:15]
	v_add_u32_e32 v234, 0x16000, v235
	v_mul_f32_e32 v252, 0xbfb8aa3b, v248
	v_mul_f32_e32 v254, v248, v248
	v_rcp_f32_e32 v254, v254
	v_pk_mul_f32 v[8:9], v[12:13], v[8:9]
	v_pk_mul_f32 v[10:11], v[14:15], v[10:11]
	v_pk_mul_f32 v[0:1], v[4:5], v[0:1]
	v_pk_mul_f32 v[2:3], v[6:7], v[2:3]
	v_pk_mul_f32 v[12:13], v[12:13], v[252:253] op_sel_hi:[1,0]
	v_pk_mul_f32 v[14:15], v[14:15], v[252:253] op_sel_hi:[1,0]
	v_pk_mul_f32 v[4:5], v[4:5], v[252:253] op_sel_hi:[1,0]
	v_pk_mul_f32 v[6:7], v[6:7], v[252:253] op_sel_hi:[1,0]
	v_exp_f32_e32 v12, v12
	v_exp_f32_e32 v13, v13
	v_exp_f32_e32 v14, v14
	v_exp_f32_e32 v15, v15
	v_exp_f32_e32 v4, v4
	v_exp_f32_e32 v5, v5
	v_exp_f32_e32 v6, v6
	v_exp_f32_e32 v7, v7
	v_pk_fma_f32 v[12:13], v[12:13], v[254:255], v[254:255] op_sel_hi:[1,0,0]
	v_pk_fma_f32 v[14:15], v[14:15], v[254:255], v[254:255] op_sel_hi:[1,0,0]
	v_pk_fma_f32 v[4:5], v[4:5], v[254:255], v[254:255] op_sel_hi:[1,0,0]
	v_pk_fma_f32 v[6:7], v[6:7], v[254:255], v[254:255] op_sel_hi:[1,0,0]
	v_rcp_f32_e32 v12, v12
	v_rcp_f32_e32 v13, v13
	v_rcp_f32_e32 v14, v14
	v_rcp_f32_e32 v15, v15
	v_rcp_f32_e32 v4, v4
	v_rcp_f32_e32 v5, v5
	v_rcp_f32_e32 v6, v6
	v_rcp_f32_e32 v7, v7
	v_pk_mul_f32 v[8:9], v[8:9], v[12:13]
	v_pk_mul_f32 v[10:11], v[10:11], v[14:15]
	v_pk_mul_f32 v[0:1], v[0:1], v[4:5]
	v_pk_mul_f32 v[2:3], v[2:3], v[6:7]
	v_cvt_pk_bf16_f32 v8, v8, v9
	v_cvt_pk_bf16_f32 v9, v10, v11
	v_cvt_pk_bf16_f32 v10, v0, v1
	v_cvt_pk_bf16_f32 v11, v2, v3
	global_store_dwordx4 v234, v[8:11], s[14:15]
	s_waitcnt vmcnt(16)
	s_waitcnt lgkmcnt(0)
	s_barrier
	s_setprio 1
	s_waitcnt lgkmcnt(0)
	v_mfma_f32_16x16x32_bf16 v[60:63], v[160:163], v[194:197], 0
	v_mfma_f32_16x16x32_bf16 v[52:55], v[168:171], v[194:197], 0
	v_mfma_f32_16x16x32_bf16 v[44:47], v[160:163], v[202:205], 0
	v_mfma_f32_16x16x32_bf16 v[36:39], v[168:171], v[202:205], 0
	v_mfma_f32_16x16x32_bf16 v[28:31], v[160:163], v[210:213], 0
	v_mfma_f32_16x16x32_bf16 v[20:23], v[168:171], v[210:213], 0
	v_mfma_f32_16x16x32_bf16 v[12:15], v[160:163], v[218:221], 0
	v_mfma_f32_16x16x32_bf16 v[4:7], v[168:171], v[218:221], 0
	v_mfma_f32_16x16x32_bf16 v[60:63], v[164:167], v[198:201], v[60:63]
	v_mfma_f32_16x16x32_bf16 v[52:55], v[172:175], v[198:201], v[52:55]
	v_mfma_f32_16x16x32_bf16 v[44:47], v[164:167], v[206:209], v[44:47]
	v_mfma_f32_16x16x32_bf16 v[36:39], v[172:175], v[206:209], v[36:39]
	v_mfma_f32_16x16x32_bf16 v[28:31], v[164:167], v[214:217], v[28:31]
	v_mfma_f32_16x16x32_bf16 v[20:23], v[172:175], v[214:217], v[20:23]
	v_mfma_f32_16x16x32_bf16 v[12:15], v[164:167], v[222:225], v[12:15]
	v_mfma_f32_16x16x32_bf16 v[4:7], v[172:175], v[222:225], v[4:7]
	s_setprio 0
	s_setprio 1
	v_mfma_f32_16x16x32_bf16 v[56:59], v[176:179], v[194:197], 0
	v_mfma_f32_16x16x32_bf16 v[48:51], v[186:189], v[194:197], 0
	v_mfma_f32_16x16x32_bf16 v[40:43], v[176:179], v[202:205], 0
	v_mfma_f32_16x16x32_bf16 v[32:35], v[186:189], v[202:205], 0
	v_mfma_f32_16x16x32_bf16 v[24:27], v[176:179], v[210:213], 0
	v_mfma_f32_16x16x32_bf16 v[16:19], v[186:189], v[210:213], 0
	v_mfma_f32_16x16x32_bf16 v[8:11], v[176:179], v[218:221], 0
	v_mfma_f32_16x16x32_bf16 v[0:3], v[186:189], v[218:221], 0
	v_mfma_f32_16x16x32_bf16 v[56:59], v[180:183], v[198:201], v[56:59]
	v_mfma_f32_16x16x32_bf16 v[48:51], v[190:193], v[198:201], v[48:51]
	v_mfma_f32_16x16x32_bf16 v[40:43], v[180:183], v[206:209], v[40:43]
	v_mfma_f32_16x16x32_bf16 v[32:35], v[190:193], v[206:209], v[32:35]
	v_mfma_f32_16x16x32_bf16 v[24:27], v[180:183], v[214:217], v[24:27]
	v_mfma_f32_16x16x32_bf16 v[16:19], v[190:193], v[214:217], v[16:19]
	v_mfma_f32_16x16x32_bf16 v[8:11], v[180:183], v[222:225], v[8:11]
	v_mfma_f32_16x16x32_bf16 v[0:3], v[190:193], v[222:225], v[0:3]
	s_setprio 0
	s_barrier
	s_add_i32 s76, 0, 0x18000
	v_add_u32_e32 v153, s76, v147
	s_add_i32 s77, 0, 0x1c000
	ds_read_b128 v[160:163], v153
	v_xor_b32_e32 v253, 64, v153
	ds_read_b128 v[164:167], v253
	ds_read_b128 v[168:171], v153 offset:2048
	ds_read_b128 v[172:175], v253 offset:2048
	v_add_u32_e32 v153, s77, v147
	ds_read_b128 v[176:179], v153
	v_xor_b32_e32 v253, 64, v153
	ds_read_b128 v[180:183], v253
	ds_read_b128 v[186:189], v153 offset:2048
	ds_read_b128 v[190:193], v253 offset:2048
	s_add_u32 s50, s50, 0x40000
	s_addc_u32 s51, s51, 0
	s_mov_b32 m0, s59
	v_lshl_add_u64 v[232:233], s[50:51], 0, v[134:135]
	ds_read_b128 v[194:197], v150 offset:32768
	v_xor_b32_e32 v253, 64, v150
	ds_read_b128 v[198:201], v253 offset:32768
	ds_read_b128 v[202:205], v150 offset:34816
	ds_read_b128 v[206:209], v253 offset:34816
	ds_read_b128 v[210:213], v150 offset:36864
	ds_read_b128 v[214:217], v253 offset:36864
	ds_read_b128 v[218:221], v150 offset:38912
	ds_read_b128 v[222:225], v253 offset:38912
	global_load_lds_dwordx4 v[232:233], off
	v_lshl_add_u64 v[232:233], s[50:51], 0, v[130:131]
	s_mov_b32 m0, s60
	s_nop 0
	global_load_lds_dwordx4 v[232:233], off
	s_waitcnt vmcnt(12)
	s_waitcnt lgkmcnt(0)
	s_barrier
	s_setprio 1
	s_waitcnt lgkmcnt(0)
	v_mfma_f32_16x16x32_bf16 v[124:127], v[160:163], v[194:197], v[124:127]
	v_mfma_f32_16x16x32_bf16 v[124:127], v[164:167], v[198:201], v[124:127]
	v_mfma_f32_16x16x32_bf16 v[116:119], v[172:175], v[198:201], v[116:119]
	v_mfma_f32_16x16x32_bf16 v[116:119], v[168:171], v[194:197], v[116:119]
	v_mfma_f32_16x16x32_bf16 v[100:103], v[168:171], v[202:205], v[100:103]
	v_mfma_f32_16x16x32_bf16 v[100:103], v[172:175], v[206:209], v[100:103]
	v_mfma_f32_16x16x32_bf16 v[108:111], v[164:167], v[206:209], v[108:111]
	v_mfma_f32_16x16x32_bf16 v[108:111], v[160:163], v[202:205], v[108:111]
	v_mfma_f32_16x16x32_bf16 v[92:95], v[160:163], v[210:213], v[92:95]
	v_mfma_f32_16x16x32_bf16 v[92:95], v[164:167], v[214:217], v[92:95]
	v_mfma_f32_16x16x32_bf16 v[84:87], v[172:175], v[214:217], v[84:87]
	v_mfma_f32_16x16x32_bf16 v[84:87], v[168:171], v[210:213], v[84:87]
	v_mfma_f32_16x16x32_bf16 v[68:71], v[168:171], v[218:221], v[68:71]
	v_mfma_f32_16x16x32_bf16 v[68:71], v[172:175], v[222:225], v[68:71]
	v_mfma_f32_16x16x32_bf16 v[76:79], v[164:167], v[222:225], v[76:79]
	v_mfma_f32_16x16x32_bf16 v[76:79], v[160:163], v[218:221], v[76:79]
	s_setprio 0
	s_setprio 1
	v_mfma_f32_16x16x32_bf16 v[120:123], v[176:179], v[194:197], v[120:123]
	v_mfma_f32_16x16x32_bf16 v[120:123], v[180:183], v[198:201], v[120:123]
	v_mfma_f32_16x16x32_bf16 v[112:115], v[190:193], v[198:201], v[112:115]
	v_mfma_f32_16x16x32_bf16 v[112:115], v[186:189], v[194:197], v[112:115]
	v_mfma_f32_16x16x32_bf16 v[96:99], v[186:189], v[202:205], v[96:99]
	v_mfma_f32_16x16x32_bf16 v[96:99], v[190:193], v[206:209], v[96:99]
	v_mfma_f32_16x16x32_bf16 v[104:107], v[180:183], v[206:209], v[104:107]
	v_mfma_f32_16x16x32_bf16 v[104:107], v[176:179], v[202:205], v[104:107]
	v_mfma_f32_16x16x32_bf16 v[88:91], v[176:179], v[210:213], v[88:91]
	v_mfma_f32_16x16x32_bf16 v[88:91], v[180:183], v[214:217], v[88:91]
	v_mfma_f32_16x16x32_bf16 v[80:83], v[190:193], v[214:217], v[80:83]
	v_mfma_f32_16x16x32_bf16 v[80:83], v[186:189], v[210:213], v[80:83]
	v_mfma_f32_16x16x32_bf16 v[64:67], v[186:189], v[218:221], v[64:67]
	v_mfma_f32_16x16x32_bf16 v[64:67], v[190:193], v[222:225], v[64:67]
	v_mfma_f32_16x16x32_bf16 v[72:75], v[180:183], v[222:225], v[72:75]
	v_mfma_f32_16x16x32_bf16 v[72:75], v[176:179], v[218:221], v[72:75]
	s_setprio 0
	s_barrier
	s_add_i32 s50, s76, s54
	v_lshl_add_u64 v[154:155], v[154:155], 0, s[20:21]
	s_mov_b32 m0, s50
	ds_read_b128 v[194:197], v150 offset:49152
	v_xor_b32_e32 v253, 64, v150
	ds_read_b128 v[198:201], v253 offset:49152
	ds_read_b128 v[202:205], v150 offset:51200
	ds_read_b128 v[206:209], v253 offset:51200
	ds_read_b128 v[210:213], v150 offset:53248
	ds_read_b128 v[214:217], v253 offset:53248
	ds_read_b128 v[218:221], v150 offset:55296
	ds_read_b128 v[222:225], v253 offset:55296
	global_load_lds_dwordx4 v[154:155], off
	s_add_i32 m0, s50, 0x2000
	s_add_u32 s48, s48, 0x40080
	v_lshl_add_u64 v[154:155], v[226:227], 0, s[20:21]
	s_addc_u32 s49, s49, 0
	s_add_i32 s50, s77, s54
	global_load_lds_dwordx4 v[154:155], off
	v_lshl_add_u64 v[154:155], s[48:49], 0, v[132:133]
	s_mov_b32 m0, s50
	s_nop 0
	global_load_lds_dwordx4 v[154:155], off
	v_lshl_add_u64 v[154:155], s[48:49], 0, v[128:129]
	s_add_i32 m0, s50, 0x2000
	s_nop 0
	global_load_lds_dwordx4 v[154:155], off
	v_lshl_add_u64 v[154:155], v[228:229], 0, s[20:21]
	s_mov_b32 m0, s62
	s_nop 0
	global_load_lds_dwordx4 v[154:155], off
	v_lshl_add_u64 v[154:155], v[230:231], 0, s[20:21]
	s_mov_b32 m0, s63
	s_nop 0
	global_load_lds_dwordx4 v[154:155], off
	s_waitcnt vmcnt(8)
	s_waitcnt lgkmcnt(0)
	s_barrier
	s_setprio 1
	s_waitcnt lgkmcnt(0)
	v_mfma_f32_16x16x32_bf16 v[60:63], v[160:163], v[194:197], v[60:63]
	v_mfma_f32_16x16x32_bf16 v[60:63], v[164:167], v[198:201], v[60:63]
	v_mfma_f32_16x16x32_bf16 v[52:55], v[172:175], v[198:201], v[52:55]
	v_mfma_f32_16x16x32_bf16 v[52:55], v[168:171], v[194:197], v[52:55]
	v_mfma_f32_16x16x32_bf16 v[36:39], v[168:171], v[202:205], v[36:39]
	v_mfma_f32_16x16x32_bf16 v[36:39], v[172:175], v[206:209], v[36:39]
	v_mfma_f32_16x16x32_bf16 v[44:47], v[164:167], v[206:209], v[44:47]
	v_mfma_f32_16x16x32_bf16 v[44:47], v[160:163], v[202:205], v[44:47]
	v_mfma_f32_16x16x32_bf16 v[28:31], v[160:163], v[210:213], v[28:31]
	v_mfma_f32_16x16x32_bf16 v[28:31], v[164:167], v[214:217], v[28:31]
	v_mfma_f32_16x16x32_bf16 v[20:23], v[172:175], v[214:217], v[20:23]
	v_mfma_f32_16x16x32_bf16 v[20:23], v[168:171], v[210:213], v[20:23]
	v_mfma_f32_16x16x32_bf16 v[4:7], v[168:171], v[218:221], v[4:7]
	v_mfma_f32_16x16x32_bf16 v[4:7], v[172:175], v[222:225], v[4:7]
	v_mfma_f32_16x16x32_bf16 v[12:15], v[164:167], v[222:225], v[12:15]
	v_mfma_f32_16x16x32_bf16 v[12:15], v[160:163], v[218:221], v[12:15]
	s_setprio 0
	s_setprio 1
	v_mfma_f32_16x16x32_bf16 v[56:59], v[176:179], v[194:197], v[56:59]
	v_mfma_f32_16x16x32_bf16 v[56:59], v[180:183], v[198:201], v[56:59]
	v_mfma_f32_16x16x32_bf16 v[48:51], v[190:193], v[198:201], v[48:51]
	v_mfma_f32_16x16x32_bf16 v[48:51], v[186:189], v[194:197], v[48:51]
	v_mfma_f32_16x16x32_bf16 v[32:35], v[186:189], v[202:205], v[32:35]
	v_mfma_f32_16x16x32_bf16 v[32:35], v[190:193], v[206:209], v[32:35]
	v_mfma_f32_16x16x32_bf16 v[40:43], v[180:183], v[206:209], v[40:43]
	v_mfma_f32_16x16x32_bf16 v[40:43], v[176:179], v[202:205], v[40:43]
	v_mfma_f32_16x16x32_bf16 v[24:27], v[176:179], v[210:213], v[24:27]
	v_mfma_f32_16x16x32_bf16 v[24:27], v[180:183], v[214:217], v[24:27]
	v_mfma_f32_16x16x32_bf16 v[16:19], v[190:193], v[214:217], v[16:19]
	v_mfma_f32_16x16x32_bf16 v[16:19], v[186:189], v[210:213], v[16:19]
	v_mfma_f32_16x16x32_bf16 v[0:3], v[186:189], v[218:221], v[0:3]
	v_mfma_f32_16x16x32_bf16 v[0:3], v[190:193], v[222:225], v[0:3]
	v_mfma_f32_16x16x32_bf16 v[8:11], v[180:183], v[222:225], v[8:11]
	v_mfma_f32_16x16x32_bf16 v[8:11], v[176:179], v[218:221], v[8:11]
	s_setprio 0
	s_barrier
	s_add_i32 s75, s75, 2
	s_add_u32 s73, s73, 0x100
	s_addc_u32 s74, s74, 0
	s_add_u32 s46, s46, 0x100
	s_addc_u32 s47, s47, 0
	s_branch .LBB0_527

.LBB0_1096:
	s_ashr_i32 s25, s24, 31
	s_lshl_b64 s[26:27], s[24:25], 19
	s_add_u32 s26, s3, s26
	s_addc_u32 s27, s33, s27
	s_and_b64 s[28:29], s[6:7], exec
	s_cselect_b32 s25, s27, s47
	s_cselect_b32 s65, s26, s46
	s_ashr_i32 s23, s22, 31
	s_lshl_b64 s[28:29], s[22:23], 19
	s_add_u32 s28, s35, s28
	s_addc_u32 s29, s48, s29
	s_and_b64 s[66:67], s[6:7], exec
	s_cselect_b32 s66, s29, s45
	s_cselect_b32 s67, s28, s44
	s_lshl_b32 s23, s30, 8
	v_add_u32_e32 v250, s23, v148
	s_add_u32 s68, s44, 0x100
	v_ashrrev_i32_e32 v251, 31, v250
	s_addc_u32 s69, s45, 0
	v_lshl_add_u64 v[144:145], v[250:251], 4, s[12:13]
	s_add_u32 s30, s46, 0x40080
	s_addc_u32 s31, s47, 0
	s_mov_b32 s70, -2
	s_mov_b64 s[44:45], 0
	s_cmp_eq_u32 s56, 1
	s_cbranch_scc1 .Lfa_10
	v_add_u32_e32 v153, s61, v147
	ds_read_b128 v[160:163], v153
	v_xor_b32_e32 v253, 64, v153
	ds_read_b128 v[164:167], v253
	ds_read_b128 v[168:171], v153 offset:2048
	ds_read_b128 v[172:175], v253 offset:2048
	v_add_u32_e32 v153, s62, v147
	ds_read_b128 v[176:179], v153
	v_xor_b32_e32 v253, 64, v153
	ds_read_b128 v[180:183], v253
	ds_read_b128 v[184:187], v153 offset:2048
	ds_read_b128 v[188:191], v253 offset:2048
	s_add_u32 s46, s30, 0xfffc0080
	s_addc_u32 s47, s31, -1
	s_and_b64 s[44:45], s[44:45], exec
	s_cselect_b32 s47, s25, s47
	s_cselect_b32 s46, s65, s46
	s_cselect_b32 s45, s66, s69
	s_cselect_b32 s44, s67, s68
	v_lshl_add_u64 v[154:155], s[30:31], 0, v[138:139]
	s_add_i32 m0, s52, 0xc000
	ds_read_b128 v[192:195], v150
	v_xor_b32_e32 v253, 64, v150
	ds_read_b128 v[196:199], v253
	ds_read_b128 v[200:203], v150 offset:2048
	ds_read_b128 v[204:207], v253 offset:2048
	ds_read_b128 v[208:211], v150 offset:4096
	ds_read_b128 v[212:215], v253 offset:4096
	ds_read_b128 v[216:219], v150 offset:6144
	ds_read_b128 v[220:223], v253 offset:6144
	global_load_lds_dwordx4 v[154:155], off
	v_lshl_add_u64 v[154:155], s[30:31], 0, v[136:137]
	s_add_i32 m0, s52, 0xe000
	s_nop 0
	global_load_lds_dwordx4 v[154:155], off
	s_waitcnt vmcnt(12)
	s_waitcnt lgkmcnt(0)
	s_barrier
	s_setprio 1
	s_waitcnt lgkmcnt(0)
	v_mfma_f32_16x16x32_bf16 v[124:127], v[160:163], v[192:195], 0
	v_mfma_f32_16x16x32_bf16 v[116:119], v[168:171], v[192:195], 0
	v_mfma_f32_16x16x32_bf16 v[108:111], v[160:163], v[200:203], 0
	v_mfma_f32_16x16x32_bf16 v[100:103], v[168:171], v[200:203], 0
	v_mfma_f32_16x16x32_bf16 v[92:95], v[160:163], v[208:211], 0
	v_mfma_f32_16x16x32_bf16 v[84:87], v[168:171], v[208:211], 0
	v_mfma_f32_16x16x32_bf16 v[76:79], v[160:163], v[216:219], 0
	v_mfma_f32_16x16x32_bf16 v[68:71], v[168:171], v[216:219], 0
	v_mfma_f32_16x16x32_bf16 v[124:127], v[164:167], v[196:199], v[124:127]
	v_mfma_f32_16x16x32_bf16 v[116:119], v[172:175], v[196:199], v[116:119]
	v_mfma_f32_16x16x32_bf16 v[108:111], v[164:167], v[204:207], v[108:111]
	v_mfma_f32_16x16x32_bf16 v[100:103], v[172:175], v[204:207], v[100:103]
	v_mfma_f32_16x16x32_bf16 v[92:95], v[164:167], v[212:215], v[92:95]
	v_mfma_f32_16x16x32_bf16 v[84:87], v[172:175], v[212:215], v[84:87]
	v_mfma_f32_16x16x32_bf16 v[76:79], v[164:167], v[220:223], v[76:79]
	v_mfma_f32_16x16x32_bf16 v[68:71], v[172:175], v[220:223], v[68:71]
	s_setprio 0
	s_setprio 1
	v_mfma_f32_16x16x32_bf16 v[120:123], v[176:179], v[192:195], 0
	v_mfma_f32_16x16x32_bf16 v[112:115], v[184:187], v[192:195], 0
	v_mfma_f32_16x16x32_bf16 v[104:107], v[176:179], v[200:203], 0
	v_mfma_f32_16x16x32_bf16 v[96:99], v[184:187], v[200:203], 0
	v_mfma_f32_16x16x32_bf16 v[88:91], v[176:179], v[208:211], 0
	v_mfma_f32_16x16x32_bf16 v[80:83], v[184:187], v[208:211], 0
	v_mfma_f32_16x16x32_bf16 v[72:75], v[176:179], v[216:219], 0
	v_mfma_f32_16x16x32_bf16 v[64:67], v[184:187], v[216:219], 0
	v_mfma_f32_16x16x32_bf16 v[120:123], v[180:183], v[196:199], v[120:123]
	v_mfma_f32_16x16x32_bf16 v[112:115], v[188:191], v[196:199], v[112:115]
	v_mfma_f32_16x16x32_bf16 v[104:107], v[180:183], v[204:207], v[104:107]
	v_mfma_f32_16x16x32_bf16 v[96:99], v[188:191], v[204:207], v[96:99]
	v_mfma_f32_16x16x32_bf16 v[88:91], v[180:183], v[212:215], v[88:91]
	v_mfma_f32_16x16x32_bf16 v[80:83], v[188:191], v[212:215], v[80:83]
	v_mfma_f32_16x16x32_bf16 v[72:75], v[180:183], v[220:223], v[72:75]
	v_mfma_f32_16x16x32_bf16 v[64:67], v[188:191], v[220:223], v[64:67]
	s_setprio 0
	s_barrier
	v_add_u32_e32 v235, 0x84000, v235
	v_add_u32_e32 v234, 0x21800, v151
	ds_read_b128 v[236:239], v234
	ds_read_b128 v[240:243], v234 offset:256
	ds_read_b128 v[244:247], v234 offset:512
	ds_read_b128 v[248:251], v234 offset:768
	s_add_i32 s71, s61, s49
	v_lshl_add_u64 v[154:155], s[44:45], 0, v[132:133]
	s_mov_b32 m0, s71
	ds_read_b128 v[192:195], v150 offset:16384
	v_xor_b32_e32 v253, 64, v150
	ds_read_b128 v[196:199], v253 offset:16384
	ds_read_b128 v[200:203], v150 offset:18432
	ds_read_b128 v[204:207], v253 offset:18432
	ds_read_b128 v[208:211], v150 offset:20480
	ds_read_b128 v[212:215], v253 offset:20480
	ds_read_b128 v[216:219], v150 offset:22528
	ds_read_b128 v[220:223], v253 offset:22528
	global_load_lds_dwordx4 v[154:155], off
	s_add_i32 m0, s71, 0x2000
	s_add_u32 s72, s44, 0x40000
	v_lshl_add_u64 v[224:225], s[44:45], 0, v[128:129]
	s_addc_u32 s73, s45, 0
	s_add_i32 s71, s62, s49
	global_load_lds_dwordx4 v[224:225], off
	v_lshl_add_u64 v[226:227], s[72:73], 0, v[132:133]
	s_mov_b32 m0, s71
	v_lshl_add_u64 v[228:229], s[46:47], 0, v[130:131]
	global_load_lds_dwordx4 v[226:227], off
	v_lshl_add_u64 v[226:227], s[72:73], 0, v[128:129]
	s_add_i32 m0, s71, 0x2000
	s_nop 0
	global_load_lds_dwordx4 v[226:227], off
	v_lshl_add_u64 v[226:227], s[46:47], 0, v[134:135]
	s_mov_b32 m0, s52
	s_nop 0
	global_load_lds_dwordx4 v[226:227], off
	s_mov_b32 m0, s53
	s_nop 0
	global_load_lds_dwordx4 v[228:229], off
	s_waitcnt lgkmcnt(8)
	v_add_f32_e32 v236, v236, v237
	v_add_f32_e32 v238, v238, v239
	v_add_f32_e32 v240, v240, v241
	v_add_f32_e32 v242, v242, v243
	v_add_f32_e32 v244, v244, v245
	v_add_f32_e32 v246, v246, v247
	v_add_f32_e32 v248, v248, v249
	v_add_f32_e32 v250, v250, v251
	v_add_f32_e32 v236, v236, v238
	v_add_f32_e32 v240, v240, v242
	v_add_f32_e32 v244, v244, v246
	v_add_f32_e32 v248, v248, v250
	v_fmamk_f32 v236, v236, 0x3a800000, v152
	v_fmamk_f32 v240, v240, 0x3a800000, v152
	v_fmamk_f32 v244, v244, 0x3a800000, v152
	v_fmamk_f32 v248, v248, 0x3a800000, v152
	v_rsq_f32_e32 v236, v236
	v_rsq_f32_e32 v240, v240
	v_rsq_f32_e32 v244, v244
	v_rsq_f32_e32 v248, v248
	v_mul_f32_e32 v252, 0xbfb8aa3b, v236
	v_mul_f32_e32 v254, v236, v236
	v_rcp_f32_e32 v254, v254
	v_pk_mul_f32 v[56:57], v[60:61], v[56:57]
	v_pk_mul_f32 v[58:59], v[62:63], v[58:59]
	v_pk_mul_f32 v[48:49], v[52:53], v[48:49]
	v_pk_mul_f32 v[50:51], v[54:55], v[50:51]
	v_pk_mul_f32 v[60:61], v[60:61], v[252:253] op_sel_hi:[1,0]
	v_pk_mul_f32 v[62:63], v[62:63], v[252:253] op_sel_hi:[1,0]
	v_pk_mul_f32 v[52:53], v[52:53], v[252:253] op_sel_hi:[1,0]
	v_pk_mul_f32 v[54:55], v[54:55], v[252:253] op_sel_hi:[1,0]
	v_exp_f32_e32 v60, v60
	v_exp_f32_e32 v61, v61
	v_exp_f32_e32 v62, v62
	v_exp_f32_e32 v63, v63
	v_exp_f32_e32 v52, v52
	v_exp_f32_e32 v53, v53
	v_exp_f32_e32 v54, v54
	v_exp_f32_e32 v55, v55
	v_pk_fma_f32 v[60:61], v[60:61], v[254:255], v[254:255] op_sel_hi:[1,0,0]
	v_pk_fma_f32 v[62:63], v[62:63], v[254:255], v[254:255] op_sel_hi:[1,0,0]
	v_pk_fma_f32 v[52:53], v[52:53], v[254:255], v[254:255] op_sel_hi:[1,0,0]
	v_pk_fma_f32 v[54:55], v[54:55], v[254:255], v[254:255] op_sel_hi:[1,0,0]
	v_rcp_f32_e32 v60, v60
	v_rcp_f32_e32 v61, v61
	v_rcp_f32_e32 v62, v62
	v_rcp_f32_e32 v63, v63
	v_rcp_f32_e32 v52, v52
	v_rcp_f32_e32 v53, v53
	v_rcp_f32_e32 v54, v54
	v_rcp_f32_e32 v55, v55
	v_pk_mul_f32 v[56:57], v[56:57], v[60:61]
	v_pk_mul_f32 v[58:59], v[58:59], v[62:63]
	v_pk_mul_f32 v[48:49], v[48:49], v[52:53]
	v_pk_mul_f32 v[50:51], v[50:51], v[54:55]
	v_cvt_pk_bf16_f32 v56, v56, v57
	v_cvt_pk_bf16_f32 v57, v58, v59
	v_cvt_pk_bf16_f32 v58, v48, v49
	v_cvt_pk_bf16_f32 v59, v50, v51
	global_store_dwordx4 v235, v[56:59], s[10:11]
	v_add_u32_e32 v234, 0x16000, v235
	v_mul_f32_e32 v252, 0xbfb8aa3b, v240
	v_mul_f32_e32 v254, v240, v240
	v_rcp_f32_e32 v254, v254
	v_pk_mul_f32 v[40:41], v[44:45], v[40:41]
	v_pk_mul_f32 v[42:43], v[46:47], v[42:43]
	v_pk_mul_f32 v[32:33], v[36:37], v[32:33]
	v_pk_mul_f32 v[34:35], v[38:39], v[34:35]
	v_pk_mul_f32 v[44:45], v[44:45], v[252:253] op_sel_hi:[1,0]
	v_pk_mul_f32 v[46:47], v[46:47], v[252:253] op_sel_hi:[1,0]
	v_pk_mul_f32 v[36:37], v[36:37], v[252:253] op_sel_hi:[1,0]
	v_pk_mul_f32 v[38:39], v[38:39], v[252:253] op_sel_hi:[1,0]
	v_exp_f32_e32 v44, v44
	v_exp_f32_e32 v45, v45
	v_exp_f32_e32 v46, v46
	v_exp_f32_e32 v47, v47
	v_exp_f32_e32 v36, v36
	v_exp_f32_e32 v37, v37
	v_exp_f32_e32 v38, v38
	v_exp_f32_e32 v39, v39
	v_pk_fma_f32 v[44:45], v[44:45], v[254:255], v[254:255] op_sel_hi:[1,0,0]
	v_pk_fma_f32 v[46:47], v[46:47], v[254:255], v[254:255] op_sel_hi:[1,0,0]
	v_pk_fma_f32 v[36:37], v[36:37], v[254:255], v[254:255] op_sel_hi:[1,0,0]
	v_pk_fma_f32 v[38:39], v[38:39], v[254:255], v[254:255] op_sel_hi:[1,0,0]
	v_rcp_f32_e32 v44, v44
	v_rcp_f32_e32 v45, v45
	v_rcp_f32_e32 v46, v46
	v_rcp_f32_e32 v47, v47
	v_rcp_f32_e32 v36, v36
	v_rcp_f32_e32 v37, v37
	v_rcp_f32_e32 v38, v38
	v_rcp_f32_e32 v39, v39
	v_pk_mul_f32 v[40:41], v[40:41], v[44:45]
	v_pk_mul_f32 v[42:43], v[42:43], v[46:47]
	v_pk_mul_f32 v[32:33], v[32:33], v[36:37]
	v_pk_mul_f32 v[34:35], v[34:35], v[38:39]
	v_cvt_pk_bf16_f32 v40, v40, v41
	v_cvt_pk_bf16_f32 v41, v42, v43
	v_cvt_pk_bf16_f32 v42, v32, v33
	v_cvt_pk_bf16_f32 v43, v34, v35
	global_store_dwordx4 v234, v[40:43], s[10:11]
	v_add_u32_e32 v235, 0x16000, v234
	v_mul_f32_e32 v252, 0xbfb8aa3b, v244
	v_mul_f32_e32 v254, v244, v244
	v_rcp_f32_e32 v254, v254
	v_pk_mul_f32 v[24:25], v[28:29], v[24:25]
	v_pk_mul_f32 v[26:27], v[30:31], v[26:27]
	v_pk_mul_f32 v[16:17], v[20:21], v[16:17]
	v_pk_mul_f32 v[18:19], v[22:23], v[18:19]
	v_pk_mul_f32 v[28:29], v[28:29], v[252:253] op_sel_hi:[1,0]
	v_pk_mul_f32 v[30:31], v[30:31], v[252:253] op_sel_hi:[1,0]
	v_pk_mul_f32 v[20:21], v[20:21], v[252:253] op_sel_hi:[1,0]
	v_pk_mul_f32 v[22:23], v[22:23], v[252:253] op_sel_hi:[1,0]
	v_exp_f32_e32 v28, v28
	v_exp_f32_e32 v29, v29
	v_exp_f32_e32 v30, v30
	v_exp_f32_e32 v31, v31
	v_exp_f32_e32 v20, v20
	v_exp_f32_e32 v21, v21
	v_exp_f32_e32 v22, v22
	v_exp_f32_e32 v23, v23
	v_pk_fma_f32 v[28:29], v[28:29], v[254:255], v[254:255] op_sel_hi:[1,0,0]
	v_pk_fma_f32 v[30:31], v[30:31], v[254:255], v[254:255] op_sel_hi:[1,0,0]
	v_pk_fma_f32 v[20:21], v[20:21], v[254:255], v[254:255] op_sel_hi:[1,0,0]
	v_pk_fma_f32 v[22:23], v[22:23], v[254:255], v[254:255] op_sel_hi:[1,0,0]
	v_rcp_f32_e32 v28, v28
	v_rcp_f32_e32 v29, v29
	v_rcp_f32_e32 v30, v30
	v_rcp_f32_e32 v31, v31
	v_rcp_f32_e32 v20, v20
	v_rcp_f32_e32 v21, v21
	v_rcp_f32_e32 v22, v22
	v_rcp_f32_e32 v23, v23
	v_pk_mul_f32 v[24:25], v[24:25], v[28:29]
	v_pk_mul_f32 v[26:27], v[26:27], v[30:31]
	v_pk_mul_f32 v[16:17], v[16:17], v[20:21]
	v_pk_mul_f32 v[18:19], v[18:19], v[22:23]
	v_cvt_pk_bf16_f32 v24, v24, v25
	v_cvt_pk_bf16_f32 v25, v26, v27
	v_cvt_pk_bf16_f32 v26, v16, v17
	v_cvt_pk_bf16_f32 v27, v18, v19
	global_store_dwordx4 v235, v[24:27], s[10:11]
	v_add_u32_e32 v234, 0x16000, v235
	v_mul_f32_e32 v252, 0xbfb8aa3b, v248
	v_mul_f32_e32 v254, v248, v248
	v_rcp_f32_e32 v254, v254
	v_pk_mul_f32 v[8:9], v[12:13], v[8:9]
	v_pk_mul_f32 v[10:11], v[14:15], v[10:11]
	v_pk_mul_f32 v[0:1], v[4:5], v[0:1]
	v_pk_mul_f32 v[2:3], v[6:7], v[2:3]
	v_pk_mul_f32 v[12:13], v[12:13], v[252:253] op_sel_hi:[1,0]
	v_pk_mul_f32 v[14:15], v[14:15], v[252:253] op_sel_hi:[1,0]
	v_pk_mul_f32 v[4:5], v[4:5], v[252:253] op_sel_hi:[1,0]
	v_pk_mul_f32 v[6:7], v[6:7], v[252:253] op_sel_hi:[1,0]
	v_exp_f32_e32 v12, v12
	v_exp_f32_e32 v13, v13
	v_exp_f32_e32 v14, v14
	v_exp_f32_e32 v15, v15
	v_exp_f32_e32 v4, v4
	v_exp_f32_e32 v5, v5
	v_exp_f32_e32 v6, v6
	v_exp_f32_e32 v7, v7
	v_pk_fma_f32 v[12:13], v[12:13], v[254:255], v[254:255] op_sel_hi:[1,0,0]
	v_pk_fma_f32 v[14:15], v[14:15], v[254:255], v[254:255] op_sel_hi:[1,0,0]
	v_pk_fma_f32 v[4:5], v[4:5], v[254:255], v[254:255] op_sel_hi:[1,0,0]
	v_pk_fma_f32 v[6:7], v[6:7], v[254:255], v[254:255] op_sel_hi:[1,0,0]
	v_rcp_f32_e32 v12, v12
	v_rcp_f32_e32 v13, v13
	v_rcp_f32_e32 v14, v14
	v_rcp_f32_e32 v15, v15
	v_rcp_f32_e32 v4, v4
	v_rcp_f32_e32 v5, v5
	v_rcp_f32_e32 v6, v6
	v_rcp_f32_e32 v7, v7
	v_pk_mul_f32 v[8:9], v[8:9], v[12:13]
	v_pk_mul_f32 v[10:11], v[10:11], v[14:15]
	v_pk_mul_f32 v[0:1], v[0:1], v[4:5]
	v_pk_mul_f32 v[2:3], v[2:3], v[6:7]
	v_cvt_pk_bf16_f32 v8, v8, v9
	v_cvt_pk_bf16_f32 v9, v10, v11
	v_cvt_pk_bf16_f32 v10, v0, v1
	v_cvt_pk_bf16_f32 v11, v2, v3
	global_store_dwordx4 v234, v[8:11], s[10:11]
	s_waitcnt vmcnt(16)
	s_waitcnt lgkmcnt(0)
	s_barrier
	s_setprio 1
	s_waitcnt lgkmcnt(0)
	v_mfma_f32_16x16x32_bf16 v[60:63], v[160:163], v[192:195], 0
	v_mfma_f32_16x16x32_bf16 v[52:55], v[168:171], v[192:195], 0
	v_mfma_f32_16x16x32_bf16 v[44:47], v[160:163], v[200:203], 0
	v_mfma_f32_16x16x32_bf16 v[36:39], v[168:171], v[200:203], 0
	v_mfma_f32_16x16x32_bf16 v[28:31], v[160:163], v[208:211], 0
	v_mfma_f32_16x16x32_bf16 v[20:23], v[168:171], v[208:211], 0
	v_mfma_f32_16x16x32_bf16 v[12:15], v[160:163], v[216:219], 0
	v_mfma_f32_16x16x32_bf16 v[4:7], v[168:171], v[216:219], 0
	v_mfma_f32_16x16x32_bf16 v[60:63], v[164:167], v[196:199], v[60:63]
	v_mfma_f32_16x16x32_bf16 v[52:55], v[172:175], v[196:199], v[52:55]
	v_mfma_f32_16x16x32_bf16 v[44:47], v[164:167], v[204:207], v[44:47]
	v_mfma_f32_16x16x32_bf16 v[36:39], v[172:175], v[204:207], v[36:39]
	v_mfma_f32_16x16x32_bf16 v[28:31], v[164:167], v[212:215], v[28:31]
	v_mfma_f32_16x16x32_bf16 v[20:23], v[172:175], v[212:215], v[20:23]
	v_mfma_f32_16x16x32_bf16 v[12:15], v[164:167], v[220:223], v[12:15]
	v_mfma_f32_16x16x32_bf16 v[4:7], v[172:175], v[220:223], v[4:7]
	s_setprio 0
	s_setprio 1
	v_mfma_f32_16x16x32_bf16 v[56:59], v[176:179], v[192:195], 0
	v_mfma_f32_16x16x32_bf16 v[48:51], v[184:187], v[192:195], 0
	v_mfma_f32_16x16x32_bf16 v[40:43], v[176:179], v[200:203], 0
	v_mfma_f32_16x16x32_bf16 v[32:35], v[184:187], v[200:203], 0
	v_mfma_f32_16x16x32_bf16 v[24:27], v[176:179], v[208:211], 0
	v_mfma_f32_16x16x32_bf16 v[16:19], v[184:187], v[208:211], 0
	v_mfma_f32_16x16x32_bf16 v[8:11], v[176:179], v[216:219], 0
	v_mfma_f32_16x16x32_bf16 v[0:3], v[184:187], v[216:219], 0
	v_mfma_f32_16x16x32_bf16 v[56:59], v[180:183], v[196:199], v[56:59]
	v_mfma_f32_16x16x32_bf16 v[48:51], v[188:191], v[196:199], v[48:51]
	v_mfma_f32_16x16x32_bf16 v[40:43], v[180:183], v[204:207], v[40:43]
	v_mfma_f32_16x16x32_bf16 v[32:35], v[188:191], v[204:207], v[32:35]
	v_mfma_f32_16x16x32_bf16 v[24:27], v[180:183], v[212:215], v[24:27]
	v_mfma_f32_16x16x32_bf16 v[16:19], v[188:191], v[212:215], v[16:19]
	v_mfma_f32_16x16x32_bf16 v[8:11], v[180:183], v[220:223], v[8:11]
	v_mfma_f32_16x16x32_bf16 v[0:3], v[188:191], v[220:223], v[0:3]
	s_setprio 0
	s_barrier
	s_add_i32 s71, 0, 0x18000
	v_add_u32_e32 v153, s71, v147
	s_add_i32 s72, 0, 0x1c000
	ds_read_b128 v[160:163], v153
	v_xor_b32_e32 v253, 64, v153
	ds_read_b128 v[164:167], v253
	ds_read_b128 v[168:171], v153 offset:2048
	ds_read_b128 v[172:175], v253 offset:2048
	v_add_u32_e32 v153, s72, v147
	ds_read_b128 v[176:179], v153
	v_xor_b32_e32 v253, 64, v153
	ds_read_b128 v[180:183], v253
	ds_read_b128 v[184:187], v153 offset:2048
	ds_read_b128 v[188:191], v253 offset:2048
	s_add_u32 s46, s46, 0x40000
	s_addc_u32 s47, s47, 0
	s_mov_b32 m0, s54
	v_lshl_add_u64 v[230:231], s[46:47], 0, v[134:135]
	ds_read_b128 v[192:195], v150 offset:32768
	v_xor_b32_e32 v253, 64, v150
	ds_read_b128 v[196:199], v253 offset:32768
	ds_read_b128 v[200:203], v150 offset:34816
	ds_read_b128 v[204:207], v253 offset:34816
	ds_read_b128 v[208:211], v150 offset:36864
	ds_read_b128 v[212:215], v253 offset:36864
	ds_read_b128 v[216:219], v150 offset:38912
	ds_read_b128 v[220:223], v253 offset:38912
	global_load_lds_dwordx4 v[230:231], off
	v_lshl_add_u64 v[230:231], s[46:47], 0, v[130:131]
	s_mov_b32 m0, s55
	s_nop 0
	global_load_lds_dwordx4 v[230:231], off
	s_waitcnt vmcnt(12)
	s_waitcnt lgkmcnt(0)
	s_barrier
	s_setprio 1
	s_waitcnt lgkmcnt(0)
	v_mfma_f32_16x16x32_bf16 v[124:127], v[160:163], v[192:195], v[124:127]
	v_mfma_f32_16x16x32_bf16 v[124:127], v[164:167], v[196:199], v[124:127]
	v_mfma_f32_16x16x32_bf16 v[116:119], v[172:175], v[196:199], v[116:119]
	v_mfma_f32_16x16x32_bf16 v[116:119], v[168:171], v[192:195], v[116:119]
	v_mfma_f32_16x16x32_bf16 v[100:103], v[168:171], v[200:203], v[100:103]
	v_mfma_f32_16x16x32_bf16 v[100:103], v[172:175], v[204:207], v[100:103]
	v_mfma_f32_16x16x32_bf16 v[108:111], v[164:167], v[204:207], v[108:111]
	v_mfma_f32_16x16x32_bf16 v[108:111], v[160:163], v[200:203], v[108:111]
	v_mfma_f32_16x16x32_bf16 v[92:95], v[160:163], v[208:211], v[92:95]
	v_mfma_f32_16x16x32_bf16 v[92:95], v[164:167], v[212:215], v[92:95]
	v_mfma_f32_16x16x32_bf16 v[84:87], v[172:175], v[212:215], v[84:87]
	v_mfma_f32_16x16x32_bf16 v[84:87], v[168:171], v[208:211], v[84:87]
	v_mfma_f32_16x16x32_bf16 v[68:71], v[168:171], v[216:219], v[68:71]
	v_mfma_f32_16x16x32_bf16 v[68:71], v[172:175], v[220:223], v[68:71]
	v_mfma_f32_16x16x32_bf16 v[76:79], v[164:167], v[220:223], v[76:79]
	v_mfma_f32_16x16x32_bf16 v[76:79], v[160:163], v[216:219], v[76:79]
	s_setprio 0
	s_setprio 1
	v_mfma_f32_16x16x32_bf16 v[120:123], v[176:179], v[192:195], v[120:123]
	v_mfma_f32_16x16x32_bf16 v[120:123], v[180:183], v[196:199], v[120:123]
	v_mfma_f32_16x16x32_bf16 v[112:115], v[188:191], v[196:199], v[112:115]
	v_mfma_f32_16x16x32_bf16 v[112:115], v[184:187], v[192:195], v[112:115]
	v_mfma_f32_16x16x32_bf16 v[96:99], v[184:187], v[200:203], v[96:99]
	v_mfma_f32_16x16x32_bf16 v[96:99], v[188:191], v[204:207], v[96:99]
	v_mfma_f32_16x16x32_bf16 v[104:107], v[180:183], v[204:207], v[104:107]
	v_mfma_f32_16x16x32_bf16 v[104:107], v[176:179], v[200:203], v[104:107]
	v_mfma_f32_16x16x32_bf16 v[88:91], v[176:179], v[208:211], v[88:91]
	v_mfma_f32_16x16x32_bf16 v[88:91], v[180:183], v[212:215], v[88:91]
	v_mfma_f32_16x16x32_bf16 v[80:83], v[188:191], v[212:215], v[80:83]
	v_mfma_f32_16x16x32_bf16 v[80:83], v[184:187], v[208:211], v[80:83]
	v_mfma_f32_16x16x32_bf16 v[64:67], v[184:187], v[216:219], v[64:67]
	v_mfma_f32_16x16x32_bf16 v[64:67], v[188:191], v[220:223], v[64:67]
	v_mfma_f32_16x16x32_bf16 v[72:75], v[180:183], v[220:223], v[72:75]
	v_mfma_f32_16x16x32_bf16 v[72:75], v[176:179], v[216:219], v[72:75]
	s_setprio 0
	s_barrier
	s_add_i32 s46, s71, s49
	v_lshl_add_u64 v[154:155], v[154:155], 0, s[14:15]
	s_mov_b32 m0, s46
	ds_read_b128 v[192:195], v150 offset:49152
	v_xor_b32_e32 v253, 64, v150
	ds_read_b128 v[196:199], v253 offset:49152
	ds_read_b128 v[200:203], v150 offset:51200
	ds_read_b128 v[204:207], v253 offset:51200
	ds_read_b128 v[208:211], v150 offset:53248
	ds_read_b128 v[212:215], v253 offset:53248
	ds_read_b128 v[216:219], v150 offset:55296
	ds_read_b128 v[220:223], v253 offset:55296
	global_load_lds_dwordx4 v[154:155], off
	s_add_i32 m0, s46, 0x2000
	s_add_u32 s44, s44, 0x40080
	v_lshl_add_u64 v[154:155], v[224:225], 0, s[14:15]
	s_addc_u32 s45, s45, 0
	s_add_i32 s46, s72, s49
	global_load_lds_dwordx4 v[154:155], off
	v_lshl_add_u64 v[154:155], s[44:45], 0, v[132:133]
	s_mov_b32 m0, s46
	s_nop 0
	global_load_lds_dwordx4 v[154:155], off
	v_lshl_add_u64 v[154:155], s[44:45], 0, v[128:129]
	s_add_i32 m0, s46, 0x2000
	s_nop 0
	global_load_lds_dwordx4 v[154:155], off
	v_lshl_add_u64 v[154:155], v[226:227], 0, s[14:15]
	s_mov_b32 m0, s57
	s_nop 0
	global_load_lds_dwordx4 v[154:155], off
	v_lshl_add_u64 v[154:155], v[228:229], 0, s[14:15]
	s_mov_b32 m0, s58
	s_nop 0
	global_load_lds_dwordx4 v[154:155], off
	s_waitcnt vmcnt(8)
	s_waitcnt lgkmcnt(0)
	s_barrier
	s_setprio 1
	s_waitcnt lgkmcnt(0)
	v_mfma_f32_16x16x32_bf16 v[60:63], v[160:163], v[192:195], v[60:63]
	v_mfma_f32_16x16x32_bf16 v[60:63], v[164:167], v[196:199], v[60:63]
	v_mfma_f32_16x16x32_bf16 v[52:55], v[172:175], v[196:199], v[52:55]
	v_mfma_f32_16x16x32_bf16 v[52:55], v[168:171], v[192:195], v[52:55]
	v_mfma_f32_16x16x32_bf16 v[36:39], v[168:171], v[200:203], v[36:39]
	v_mfma_f32_16x16x32_bf16 v[36:39], v[172:175], v[204:207], v[36:39]
	v_mfma_f32_16x16x32_bf16 v[44:47], v[164:167], v[204:207], v[44:47]
	v_mfma_f32_16x16x32_bf16 v[44:47], v[160:163], v[200:203], v[44:47]
	v_mfma_f32_16x16x32_bf16 v[28:31], v[160:163], v[208:211], v[28:31]
	v_mfma_f32_16x16x32_bf16 v[28:31], v[164:167], v[212:215], v[28:31]
	v_mfma_f32_16x16x32_bf16 v[20:23], v[172:175], v[212:215], v[20:23]
	v_mfma_f32_16x16x32_bf16 v[20:23], v[168:171], v[208:211], v[20:23]
	v_mfma_f32_16x16x32_bf16 v[4:7], v[168:171], v[216:219], v[4:7]
	v_mfma_f32_16x16x32_bf16 v[4:7], v[172:175], v[220:223], v[4:7]
	v_mfma_f32_16x16x32_bf16 v[12:15], v[164:167], v[220:223], v[12:15]
	v_mfma_f32_16x16x32_bf16 v[12:15], v[160:163], v[216:219], v[12:15]
	s_setprio 0
	s_setprio 1
	v_mfma_f32_16x16x32_bf16 v[56:59], v[176:179], v[192:195], v[56:59]
	v_mfma_f32_16x16x32_bf16 v[56:59], v[180:183], v[196:199], v[56:59]
	v_mfma_f32_16x16x32_bf16 v[48:51], v[188:191], v[196:199], v[48:51]
	v_mfma_f32_16x16x32_bf16 v[48:51], v[184:187], v[192:195], v[48:51]
	v_mfma_f32_16x16x32_bf16 v[32:35], v[184:187], v[200:203], v[32:35]
	v_mfma_f32_16x16x32_bf16 v[32:35], v[188:191], v[204:207], v[32:35]
	v_mfma_f32_16x16x32_bf16 v[40:43], v[180:183], v[204:207], v[40:43]
	v_mfma_f32_16x16x32_bf16 v[40:43], v[176:179], v[200:203], v[40:43]
	v_mfma_f32_16x16x32_bf16 v[24:27], v[176:179], v[208:211], v[24:27]
	v_mfma_f32_16x16x32_bf16 v[24:27], v[180:183], v[212:215], v[24:27]
	v_mfma_f32_16x16x32_bf16 v[16:19], v[188:191], v[212:215], v[16:19]
	v_mfma_f32_16x16x32_bf16 v[16:19], v[184:187], v[208:211], v[16:19]
	v_mfma_f32_16x16x32_bf16 v[0:3], v[184:187], v[216:219], v[0:3]
	v_mfma_f32_16x16x32_bf16 v[0:3], v[188:191], v[220:223], v[0:3]
	v_mfma_f32_16x16x32_bf16 v[8:11], v[180:183], v[220:223], v[8:11]
	v_mfma_f32_16x16x32_bf16 v[8:11], v[176:179], v[216:219], v[8:11]
	s_setprio 0
	s_barrier
	s_add_i32 s70, s70, 2
	s_add_u32 s68, s68, 0x100
	s_addc_u32 s69, s69, 0
	s_add_u32 s30, s30, 0x100
	s_addc_u32 s31, s31, 0
	s_branch .LBB0_1098
